# gla state and output passes fetch the next chunk operands into spare registers during the current chunk (no load wait at chunk start)
# speedup vs baseline: 1.0241x; 1.0020x over previous
; #define LAS __attribute__((address_space(3)))
; template <int MODE>
; __device__ __forceinline__ void gla_item(const int TID, const Params& p, int l, int ci, int head, LAS unsigned char* lds, const float (&wg)[2][16], const float (&bg)[2], const float (&ngv)[16]) {
;     const int tid = TID, lane = tid & 63, wid = tid >> 6;
;     const bf16_t* cols = (const bf16_t*)(p.ws + WS_COLS);
;     int seq, c; chunk_info(ci, seq, c);
;     const int tok0 = seq_start(seq) + (c == 0 ? -48 : 16 + 64 * (c - 1));
;     const int rmin = (c == 0) ? 48 : 0;
;     LAS float* glr_s = (LAS float*)(lds + GL_GLR); LAS float* bfs = (LAS float*)(lds + GL_BF); LAS float* bbs = (LAS float*)(lds + GL_BB);
;     f32x4 gbv[4];
;     if (MODE == 1) { const float* gb = (const float*)(p.ws + WS_GB) + (size_t)(ci * 4 + head) * 8192;
; #pragma unroll
;       for (int i = 0; i < 4; ++i) gbv[i] = *(const f32x4*)(gb + (i * 512 + tid) * 4); }
;     u32x4 kw = (u32x4){0u, 0u, 0u, 0u}, qw = kw, vwp[2], gwp[2];
;     { const int r = tid >> 3, k8 = (tid & 7) * 8; const int rc = r >= rmin ? r : rmin; const bf16_t* rowp = cols + (size_t)(tok0 + rc) * NINP;
;       kw = *(const u32x4*)(rowp + C_K + head * 64 + k8); if (MODE == 1) qw = *(const u32x4*)(rowp + C_Q + head * 64 + k8);
; #pragma unroll
;       for (int hh = 0; hh < 2; ++hh) { vwp[hh] = *(const u32x4*)(rowp + C_V + head * 128 + ((tid & 7) + 8 * hh) * 8); if (MODE == 1) gwp[hh] = *(const u32x4*)(rowp + C_GB + head * 128 + (tid & 7) * 16 + hh * 8); } }
; __global__ void __launch_bounds__(512) fwd_megakernel(Params p_in) {
;     ...
;                 { const int head_ = ((b + 128) % G) & 3, kk_ = TID & 63; float wg_[2][16], bg_[2];
;                   _Pragma("unroll") for (int d = 0; d < 2; ++d) { bg_[d] = p.in[16][(l * 2 + d) * 256 + head_ * 64 + kk_]; _Pragma("unroll") for (int j = 0; j < 16; ++j) wg_[d][j] = p.in[15][((size_t)(l * 2 + d) * 16 + j) * 256 + head_ * 64 + kk_]; }
;                   float ng_[16]; _Pragma("unroll") for (int e = 0; e < 16; ++e) ng_[e] = p.in[17][l * 512 + head_ * 128 + (TID & 7) * 16 + e];
;                   for (int it = (b + 128) % G; it < NCK * 4; it += G) gla_item<1>(TID, p, l, it >> 2, it & 3, lds, wg_, bg_, ng_); }
.LBB0_332:
	v_and_b32_e32 v12, 0x70, v146
	s_andn2_b64 vcc, exec, s[2:3]
	s_cbranch_vccnz .LBB0_345
	s_lshl_b32 s1, s0, 7
	s_and_b32 s1, s1, 0x180
	s_or_b32 s1, s1, s20
	v_or_b32_e32 v0, s1, v12
	v_readlane_b32 s40, v254, 32
	v_ashrrev_i32_e32 v1, 31, v0
	v_readlane_b32 s42, v254, 34
	v_readlane_b32 s43, v254, 35
	v_ashrrev_i32_e32 v35, 6, v194
	v_ashrrev_i32_e32 v13, 3, v194
	v_lshl_add_u64 v[18:19], v[0:1], 2, s[42:43]
	global_load_dwordx4 v[0:3], v[18:19], off
	global_load_dwordx4 v[4:7], v[18:19], off offset:16
	global_load_dwordx4 v[8:11], v[18:19], off offset:32
	s_nop 0
	global_load_dwordx4 v[18:21], v[18:19], off offset:48
	v_and_b32_e32 v38, 7, v194
	v_ashrrev_i32_e32 v39, 7, v194
	s_movk_i32 s3, 0x90
	s_movk_i32 s2, 0x900
	v_mul_u32_u24_e32 v31, 0x48, v141
	v_lshlrev_b32_e32 v34, 4, v38
	v_lshlrev_b32_e32 v40, 5, v38
	v_mul_lo_u32 v41, v13, s3
	v_lshlrev_b32_e32 v44, 1, v13
	v_lshlrev_b32_e32 v45, 1, v35
	v_mul_lo_u32 v46, v39, s2
	v_readlane_b32 s9, v253, 44
	v_readlane_b32 s2, v253, 43
	v_lshlrev_b32_e32 v33, 1, v147
	v_bitop3_b32 v42, v35, v194, 7 bitop3:0x78
	v_lshlrev_b32_e32 v48, 1, v31
	v_lshl_or_b32 v40, v13, 8, v40
	v_add3_u32 v84, 0, v41, v34
	v_add3_u32 v85, s9, v41, v34
	v_add3_u32 v86, s2, v41, v34
	v_and_b32_e32 v41, 14, v44
	v_and_b32_e32 v45, 2, v45
	v_lshrrev_b32_e32 v37, 2, v194
	v_mul_u32_u24_e32 v43, 0x480, v38
	v_add3_u32 v50, s9, v33, v48
	v_add_u32_e32 v87, 0, v40
	v_lshl_or_b32 v40, v42, 4, v41
	v_mul_u32_u24_e32 v41, 0x480, v45
	v_readlane_b32 s9, v253, 45
	v_and_b32_e32 v47, 12, v37
	v_add_u32_e32 v49, 0, v46
	v_add3_u32 v90, s9, v43, v40
	v_lshlrev_b32_e32 v40, 1, v41
	v_add3_u32 v52, s2, v33, v48
	v_lshl_or_b32 v39, v39, 4, v47
	v_add3_u32 v89, v49, v48, v33
	v_lshl_or_b32 v42, v45, 4, v141
	v_readlane_b32 s48, v254, 40
	v_readlane_b32 s49, v254, 41
	v_readlane_b32 s50, v254, 42
	v_readlane_b32 s51, v254, 43
	v_readlane_b32 s41, v254, 33
	v_readlane_b32 s44, v254, 36
	v_readlane_b32 s45, v254, 37
	v_readlane_b32 s46, v254, 38
	v_readlane_b32 s47, v254, 39
	v_or_b32_e32 v45, 1, v39
	v_or_b32_e32 v54, 2, v39
	v_readlane_b32 s10, v253, 46
	s_add_i32 s1, 0, 0x20400
	s_add_i32 s8, 0, 0x1bc00
	v_lshlrev_b32_e32 v24, 3, v194
	v_lshl_add_u32 v41, v42, 1, s10
	v_cmp_gt_i32_e64 s[38:39], v42, v39
	v_cmp_lt_i32_e64 s[40:41], v42, v39
	v_cmp_gt_i32_e64 s[42:43], v42, v45
	v_cmp_gt_i32_e64 s[44:45], v42, v54
	v_cmp_lt_i32_e64 s[46:47], v42, v54
	v_add_u32_e32 v36, 0x1000, v24
	v_add_u32_e32 v91, v50, v40
	v_add_u32_e32 v92, v52, v40
	v_bfe_i32 v29, v194, 3, 26
	v_ashrrev_i32_e32 v44, 6, v36
	s_add_u32 s2, s94, 0x12300000
	v_bfe_u32 v80, v194, 4, 2
	v_readlane_b32 s52, v254, 44
	v_readlane_b32 s53, v254, 45
	v_readlane_b32 s54, v254, 46
	v_readlane_b32 s55, v254, 47
	v_lshlrev_b32_e32 v22, 2, v194
	v_mul_lo_u32 v82, v29, s3
	v_mul_lo_u32 v88, v44, s3
	v_mul_lo_u32 v44, v39, s3
	s_addc_u32 s3, s95, 0
	v_lshrrev_b32_e32 v43, 3, v141
	v_bfe_u32 v56, v194, 3, 1
	s_waitcnt vmcnt(3)
	v_mov_b32_e32 v49, v2
	v_add_u32_e32 v2, 0x900, v40
	v_mov_b32_e32 v47, v0
	v_or_b32_e32 v0, 3, v39
	v_add_u32_e32 v93, v50, v2
	v_add_u32_e32 v94, v52, v2
	v_or_b32_e32 v2, 16, v42
	v_cmp_gt_i32_e64 s[48:49], v42, v0
	v_cmp_lt_i32_e64 s[50:51], v42, v0
	v_cmp_gt_i32_e64 s[62:63], v2, v0
	v_cmp_lt_i32_e64 s[64:65], v2, v0
	v_lshlrev_b32_e32 v0, 2, v35
	v_and_b32_e32 v0, 4, v0
	v_mul_u32_u24_e32 v42, 0x480, v0
	s_waitcnt vmcnt(2)
	v_mov_b32_e32 v53, v6
	v_add_u32_e32 v6, s9, v48
	v_add3_u32 v35, s8, v33, v48
	v_add3_u32 v33, s1, v33, v48
	v_lshlrev_b32_e32 v40, 2, v141
	v_lshlrev_b32_e32 v42, 1, v42
	v_lshlrev_b32_e32 v0, 6, v0
	v_cmp_gt_i32_e64 s[56:57], v2, v45
	v_add_u32_e32 v45, v6, v42
	v_add_u32_e32 v95, v35, v42
	v_add_u32_e32 v96, v33, v42
	v_add3_u32 v97, 0, v40, v0
	s_movk_i32 s1, 0x210
	v_add_u32_e32 v0, 0x900, v42
	v_add_u32_e32 v50, 0x1200, v42
	v_add_u32_e32 v42, 0x1b00, v42
	s_waitcnt vmcnt(1)
	v_mov_b32_e32 v55, v8
	s_waitcnt vmcnt(0)
	v_mov_b32_e32 v59, v18
	v_lshrrev_b32_e32 v8, 4, v194
	v_or_b32_e32 v18, 4, v80
	v_mul_lo_u32 v98, v39, s1
	v_add_u32_e32 v99, v35, v0
	v_add_u32_e32 v101, v35, v50
	v_add_u32_e32 v103, v35, v42
	v_mul_lo_u32 v35, v13, s1
	s_ashr_i32 s1, s0, 31
	v_add_u32_e32 v27, 0, v12
	v_add_u32_e32 v26, 0x800, v22
	v_add_u32_e32 v28, 0x1000, v22
	v_add_u32_e32 v30, 0x1800, v22
	v_ashrrev_i32_e32 v25, 31, v24
	v_mov_b32_e32 v51, v4
	v_mov_b32_e32 v61, v20
	v_lshl_add_u32 v4, v2, 1, s10
	v_cmp_gt_i32_e64 s[52:53], v2, v39
	v_cmp_lt_i32_e64 s[54:55], v2, v39
	v_cmp_gt_i32_e64 s[58:59], v2, v54
	v_cmp_lt_i32_e64 s[60:61], v2, v54
	v_add3_u32 v2, s10, v46, v48
	v_lshlrev_b32_e32 v20, 4, v18
	v_bitop3_b32 v8, v43, v8, 3 bitop3:0x78
	v_bitop3_b32 v46, v80, v43, 4 bitop3:0x36
	v_bitop3_b32 v40, v43, v80, 2 bitop3:0x36
	v_bitop3_b32 v48, v43, v18, 2 bitop3:0x36
	v_bitop3_b32 v54, v43, v80, 4 bitop3:0x36
	v_bitop3_b32 v43, v43, v80, 4 bitop3:0x14
	v_bitop3_b32 v58, v56, v80, 6 bitop3:0x36
	v_bitop3_b32 v18, v56, v18, 6 bitop3:0x36
	s_lshl_b64 s[8:9], s[0:1], 15
	v_ashrrev_i32_e32 v23, 31, v22
	v_lshlrev_b32_e32 v32, 3, v38
	v_add_u32_e32 v81, 0x1bc00, v27
	v_add_u32_e32 v83, 0x20400, v27
	v_ashrrev_i32_e32 v27, 31, v26
	v_ashrrev_i32_e32 v29, 31, v28
	v_ashrrev_i32_e32 v31, 31, v30
	v_ashrrev_i32_e32 v37, 31, v36
	v_mov_b32_e32 v57, v10
	v_and_b32_e32 v10, 48, v194
	v_lshlrev_b32_e32 v8, 4, v8
	v_lshlrev_b32_e32 v46, 4, v46
	v_add_u32_e32 v39, v6, v0
	v_lshlrev_b32_e32 v40, 4, v40
	v_lshlrev_b32_e32 v48, 4, v48
	v_add_u32_e32 v100, v33, v0
	v_add_u32_e32 v0, 64, v97
	v_add_u32_e32 v52, v6, v50
	v_lshlrev_b32_e32 v54, 4, v54
	v_lshlrev_b32_e32 v43, 4, v43
	v_add_u32_e32 v102, v33, v50
	v_add_u32_e32 v50, 0x80, v97
	v_add_u32_e32 v6, v6, v42
	v_lshlrev_b32_e32 v58, 4, v58
	v_lshlrev_b32_e32 v18, 4, v18
	v_add_u32_e32 v104, v33, v42
	v_add_u32_e32 v33, 0xc0, v97
	v_lshlrev_b32_e32 v38, 6, v38
	s_add_u32 s28, s94, s8
	v_lshlrev_b64 v[64:65], 1, v[24:25]
	v_mov_b64_e32 v[24:25], 0x4cfc4600
	v_add3_u32 v105, 0, v35, v38
	v_lshlrev_b64 v[62:63], 1, v[36:37]
	s_addc_u32 s29, s95, s9
	v_lshl_add_u64 v[66:67], v[30:31], 2, v[24:25]
	v_lshl_add_u64 v[68:69], v[28:29], 2, v[24:25]
	v_lshl_add_u64 v[70:71], v[26:27], 2, v[24:25]
	v_lshl_add_u64 v[72:73], v[22:23], 2, v[24:25]
	v_lshlrev_b32_e32 v74, 1, v32
	v_lshlrev_b32_e32 v182, 1, v34
	v_add_u32_e32 v106, v41, v44
	v_add_u32_e32 v107, v4, v44
	v_add_u32_e32 v108, v2, v10
	v_add_u32_e32 v109, v45, v8
	v_add_u32_e32 v110, v2, v20
	v_add_u32_e32 v111, v45, v46
	v_add_u32_e32 v112, v39, v40
	v_add_u32_e32 v113, v39, v48
	v_add_u32_e32 v114, v0, v98
	v_add_u32_e32 v115, v52, v54
	v_add_u32_e32 v116, v52, v43
	v_add_u32_e32 v117, v50, v98
	v_add_u32_e32 v118, v6, v58
	v_add_u32_e32 v119, v6, v18
	v_add_u32_e32 v120, v33, v98
	s_mov_b32 s68, 0
	s_branch .LBB0_335

; template <int MODE>
; __device__ __forceinline__ void gla_item(const int TID, const Params& p, int l, int ci, int head, LAS unsigned char* lds, const float (&wg)[2][16], const float (&bg)[2], const float (&ngv)[16]) {
;     ...
;     if (MODE == 1) { const float* gb = (const float*)(p.ws + WS_GB) + (size_t)(ci * 4 + head) * 8192;
; #pragma unroll
;       for (int i = 0; i < 4; ++i) gbv[i] = *(const f32x4*)(gb + (i * 512 + tid) * 4); }
;     u32x4 kw = (u32x4){0u, 0u, 0u, 0u}, qw = kw, vwp[2], gwp[2];
;     { const int r = tid >> 3, k8 = (tid & 7) * 8; const int rc = r >= rmin ? r : rmin; const bf16_t* rowp = cols + (size_t)(tok0 + rc) * NINP;
;       kw = *(const u32x4*)(rowp + C_K + head * 64 + k8); if (MODE == 1) qw = *(const u32x4*)(rowp + C_Q + head * 64 + k8);
; #pragma unroll
;       for (int hh = 0; hh < 2; ++hh) { vwp[hh] = *(const u32x4*)(rowp + C_V + head * 128 + ((tid & 7) + 8 * hh) * 8); if (MODE == 1) gwp[hh] = *(const u32x4*)(rowp + C_GB + head * 128 + (tid & 7) * 16 + hh * 8); } }
;     ...
;     if (MODE == 1) {
;         const bf16_t* spb = (const bf16_t*)(p.ws + WS_SPB); u32x4 sv[2][2];
; #pragma unroll
;         for (int d = 0; d < 2; ++d) { const bf16_t* src = spb + ((size_t)(ci * 4 + head) * 2 + d) * 8192;
; #pragma unroll
;             for (int i = 0; i < 2; ++i) sv[d][i] = *(const u32x4*)(src + (i * 512 + tid) * 8); }
.LBB0_340:
	v_lshl_add_u64 v[22:23], s[28:29], 0, v[72:73]
	s_lshl_b32 s1, s21, 6
	v_lshl_add_u64 v[24:25], s[28:29], 0, v[70:71]
	s_cmp_lg_u32 s68, 0
	s_cbranch_scc1 .Lgq_ma
	flat_load_dwordx4 v[38:41], v[22:23]
	flat_load_dwordx4 v[42:45], v[24:25]
	s_branch .Lgq_da
.Lgq_ma:
	v_mov_b32_e32 v38, v196
	v_mov_b32_e32 v39, v197
	v_mov_b32_e32 v40, v198
	v_mov_b32_e32 v41, v199
	v_mov_b32_e32 v42, v200
	v_mov_b32_e32 v43, v201
	v_mov_b32_e32 v44, v202
	v_mov_b32_e32 v45, v203
.Lgq_da:
	v_lshl_add_u64 v[22:23], s[28:29], 0, v[68:69]
	s_add_i32 s1, s1, s23
	v_lshl_add_u64 v[24:25], s[28:29], 0, v[66:67]
	s_cmp_lg_u32 s68, 0
	s_cbranch_scc1 .Lgq_mb
	flat_load_dwordx4 v[76:79], v[22:23]
	flat_load_dwordx4 v[122:125], v[24:25]
	s_branch .Lgq_db
.Lgq_mb:
	v_mov_b32_e32 v76, v204
	v_mov_b32_e32 v77, v205
	v_mov_b32_e32 v78, v206
	v_mov_b32_e32 v79, v207
	v_mov_b32_e32 v122, v208
	v_mov_b32_e32 v123, v209
	v_mov_b32_e32 v124, v210
	v_mov_b32_e32 v125, v211
.Lgq_db:
	s_and_b32 s10, s0, 3
	s_sub_i32 s1, s1, 48
	s_cmp_eq_u32 s21, 0
	s_cselect_b32 s21, 48, 0
	v_max_i32_e32 v0, s21, v13
	v_mov_b64_e32 v[22:23], s[2:3]
	v_add_u32_e32 v0, s1, v0
	s_lshl_b32 s24, s10, 7
	v_mad_i64_i32 v[22:23], s[8:9], v0, s4, v[22:23]
	v_mov_b32_e32 v75, v183
	v_lshl_add_u64 v[24:25], v[22:23], 0, s[24:25]
	v_lshl_add_u64 v[24:25], v[24:25], 0, v[74:75]
	s_cmp_lg_u32 s68, 0
	s_cbranch_scc1 .Lgq_mc
	flat_load_dwordx4 v[126:129], v[24:25] offset:2048
	flat_load_dwordx4 v[130:133], v[24:25] offset:2560
	s_branch .Lgq_dc
.Lgq_mc:
	v_mov_b32_e32 v126, v212
	v_mov_b32_e32 v127, v213
	v_mov_b32_e32 v128, v214
	v_mov_b32_e32 v129, v215
	v_mov_b32_e32 v130, v216
	v_mov_b32_e32 v131, v217
	v_mov_b32_e32 v132, v218
	v_mov_b32_e32 v133, v219
.Lgq_dc:
	s_mov_b32 s9, s25
	s_lshl_b32 s8, s10, 8
	v_lshl_add_u64 v[22:23], v[22:23], 0, s[8:9]
	v_lshl_add_u64 v[24:25], v[22:23], 0, v[182:183]
	s_mov_b64 s[8:9], 0x1000
	v_lshl_add_u64 v[134:135], v[24:25], 0, s[8:9]
	s_movk_i32 s8, 0x1000
	v_add_co_u32_e32 v24, vcc, s8, v24
	v_add_u32_e32 v0, 0, v146
	v_lshl_add_u64 v[22:23], v[22:23], 0, v[74:75]
	v_addc_co_u32_e32 v25, vcc, 0, v25, vcc
	s_cmp_lg_u32 s68, 0
	s_cbranch_scc1 .Lgq_md
	flat_load_dwordx4 v[26:29], v[24:25]
	flat_load_dwordx4 v[30:33], v[22:23] offset:3200
	flat_load_dwordx4 v[34:37], v[22:23] offset:3072
	s_nop 0
	flat_load_dwordx4 v[22:25], v[134:135] offset:16
	s_branch .Lgq_dd
.Lgq_md:
	v_mov_b32_e32 v26, v236
	v_mov_b32_e32 v27, v237
	v_mov_b32_e32 v28, v238
	v_mov_b32_e32 v29, v239
	v_mov_b32_e32 v30, v240
	v_mov_b32_e32 v31, v241
	v_mov_b32_e32 v32, v242
	v_mov_b32_e32 v33, v243
	v_mov_b32_e32 v34, v244
	v_mov_b32_e32 v35, v245
	v_mov_b32_e32 v36, v246
	v_mov_b32_e32 v37, v247
	v_mov_b32_e32 v22, v170
	v_mov_b32_e32 v23, v171
	v_mov_b32_e32 v24, v172
	v_mov_b32_e32 v25, v173
.Lgq_dd:
	s_cmp_lg_u32 s68, 0
	s_cbranch_scc1 .Lgq_me
	v_add_u32_e32 v166, 0x50104000, v64
	v_add_u32_e32 v167, 0x50104000, v62
	v_add_u32_e32 v168, 0x50108000, v64
	v_add_u32_e32 v169, 0x50108000, v62
	global_load_dwordx4 v[150:153], v166, s[28:29] offset:1536
	global_load_dwordx4 v[154:157], v167, s[28:29] offset:1536
	global_load_dwordx4 v[158:161], v168, s[28:29] offset:1536
	global_load_dwordx4 v[162:165], v169, s[28:29] offset:1536
	s_branch .Lgq_de
.Lgq_me:
	v_mov_b32_e32 v150, v174
	v_mov_b32_e32 v151, v175
	v_mov_b32_e32 v152, v176
	v_mov_b32_e32 v153, v177
	v_mov_b32_e32 v154, v178
	v_mov_b32_e32 v155, v179
	v_mov_b32_e32 v156, v180
	v_mov_b32_e32 v157, v181
	v_mov_b32_e32 v158, v136
	v_mov_b32_e32 v159, v137
	v_mov_b32_e32 v160, v138
	v_mov_b32_e32 v161, v139
	v_mov_b32_e32 v162, v186
	v_mov_b32_e32 v163, v187
	v_mov_b32_e32 v164, v188
	v_mov_b32_e32 v165, v189
.Lgq_de:
	s_waitcnt lgkmcnt(0)
	s_barrier
	v_cmp_gt_i32_e32 vcc, s21, v13
	s_mov_b32 s8, 0x50104000
	s_cmp_lg_u32 s68, 0
	s_cbranch_scc1 .Lgq_nodrain
	s_waitcnt vmcnt(0)
.Lgq_nodrain:
	s_mov_b32 s68, 0
	s_add_i32 s69, s0, s96
	s_cmpk_gt_i32 s69, 0x627
	s_cbranch_scc1 .Lgq_nopf
	s_ashr_i32 s70, s69, 2
	s_cmpk_lt_i32 s70, 0x82
	s_cbranch_scc1 .Lgq_a
	s_sub_i32 s71, s70, 0x82
	s_mul_i32 s72, s71, 0x7c2
	s_lshr_b32 s72, s72, 16
	s_mul_i32 s73, s72, 33
	s_sub_i32 s71, s71, s73
	s_mul_i32 s73, s72, 0x810
	s_add_i32 s73, s73, 0x2020
	s_branch .Lgq_c
.Lgq_a:
	s_cmpk_ge_i32 s70, 65
	s_cselect_b32 s72, 65, 0
	s_cselect_b32 s73, 0x1010, 0
	s_sub_i32 s71, s70, s72
.Lgq_c:
	s_lshl_b32 s72, s71, 6
	s_add_i32 s73, s73, s72
	s_sub_i32 s73, s73, 48
	s_cmp_eq_u32 s71, 0
	s_cselect_b32 s74, 48, 0
	v_max_i32_e32 v140, s74, v13
	v_add_u32_e32 v140, s73, v140
	v_mul_lo_u32 v140, v140, s4
	s_and_b32 s75, s0, 3
	s_lshl_b32 s76, s75, 7
	s_lshl_b32 s77, s75, 8
	v_add3_u32 v142, v140, s76, v74
	v_add3_u32 v143, v140, s77, v74
	v_add3_u32 v144, v140, s77, v182
	v_add_u32_e32 v144, 0x1000, v144
	s_add_u32 s78, s28, s26
	s_addc_u32 s79, s29, s27
	global_load_dwordx4 v[196:199], v72, s[78:79]
	global_load_dwordx4 v[200:203], v70, s[78:79]
	global_load_dwordx4 v[204:207], v68, s[78:79]
	global_load_dwordx4 v[208:211], v66, s[78:79]
	global_load_dwordx4 v[212:215], v142, s[2:3] offset:2048
	global_load_dwordx4 v[216:219], v142, s[2:3] offset:2560
	global_load_dwordx4 v[236:239], v144, s[2:3]
	global_load_dwordx4 v[240:243], v143, s[2:3] offset:3200
	global_load_dwordx4 v[244:247], v143, s[2:3] offset:3072
	global_load_dwordx4 v[170:173], v144, s[2:3] offset:16
	v_add_u32_e32 v145, 0x50104000, v64
	v_add_u32_e32 v147, 0x50104000, v62
	v_add_u32_e32 v148, 0x50108000, v64
	v_add_u32_e32 v149, 0x50108000, v62
	global_load_dwordx4 v[174:177], v145, s[78:79] offset:1536
	global_load_dwordx4 v[178:181], v147, s[78:79] offset:1536
	global_load_dwordx4 v[136:139], v148, s[78:79] offset:1536
	global_load_dwordx4 v[186:189], v149, s[78:79] offset:1536
	s_mov_b32 s68, 1
; #define LAS __attribute__((address_space(3)))
; template <int MODE>
; __device__ __forceinline__ void gla_item(const int TID, const Params& p, int l, int ci, int head, LAS unsigned char* lds, const float (&wg)[2][16], const float (&bg)[2], const float (&ngv)[16]) {
;     ...
;       __syncthreads();
; #pragma unroll
;       for (int i = 0; i < 4; ++i) { const int e = (i * 512 + tid) * 4; *(LAS f32x4*)(bfs + e) = gbv[i]; }
;       __syncthreads();
;     }
;     LAS bf16_t* vT = (LAS bf16_t*)(lds + GL_VT);
;     { const int r = tid >> 3, k8 = (tid & 7) * 8; const bool ok = r >= rmin;
;       if (!ok) { kw = (u32x4){0u, 0u, 0u, 0u}; qw = kw; }
;       float qv[8], kv[8];
; #pragma unroll
;       for (int i = 0; i < 4; ++i) { qv[2 * i] = bflo(qw[i]); qv[2 * i + 1] = bfhi(qw[i]); kv[2 * i] = bflo(kw[i]); kv[2 * i + 1] = bfhi(kw[i]); }
;       if (MODE == 0) { LAS bf16_t* kd0 = (LAS bf16_t*)(lds + GL_QE0); LAS bf16_t* kd1 = (LAS bf16_t*)(lds + GL_QE1);
; #pragma unroll
;           for (int i = 0; i < 8; ++i) { const int kk = k8 + i; kd0[kk * GLD + SWZ(kk, r)] = f2bf(kv[i] * __expf(bfs[63 * 64 + kk] - bfs[r * 64 + kk])); kd1[kk * GLD + SWZ(kk, r)] = f2bf(kv[i] * __expf(bbs[kk] - bbs[r * 64 + kk])); }
;       } else { LAS bf16_t* qe0 = (LAS bf16_t*)(lds + GL_QE0); LAS bf16_t* qe1 = (LAS bf16_t*)(lds + GL_QE1); LAS bf16_t* ke0 = (LAS bf16_t*)(lds + GL_KE0); LAS bf16_t* ke1 = (LAS bf16_t*)(lds + GL_KE1);
;           u32x4 a, b2, c2, d2;
; #pragma unroll
;           for (int i = 0; i < 4; ++i) { const int kk = k8 + 2 * i; const float f0 = bfs[r * 64 + kk], f1 = bfs[r * 64 + kk + 1], g0 = bbs[r * 64 + kk], g1 = bbs[r * 64 + kk + 1];
;               a[i] = cvt_pk_bf16(qv[2 * i] * 0.125f * __expf(f0), qv[2 * i + 1] * 0.125f * __expf(f1)); b2[i] = cvt_pk_bf16(qv[2 * i] * 0.125f * __expf(g0), qv[2 * i + 1] * 0.125f * __expf(g1));
;               c2[i] = cvt_pk_bf16(kv[2 * i] * __expf(-f0), kv[2 * i + 1] * __expf(-f1)); d2[i] = cvt_pk_bf16(kv[2 * i] * __expf(-g0), kv[2 * i + 1] * __expf(-g1)); }
;           *(LAS u32x4*)(qe0 + r * GLD + k8) = a; *(LAS u32x4*)(qe1 + r * GLD + k8) = b2; *(LAS u32x4*)(ke0 + r * GLD + k8) = c2; *(LAS u32x4*)(ke1 + r * GLD + k8) = d2; }
; #pragma unroll
;       for (int hh = 0; hh < 2; ++hh) { const int v8 = ((tid & 7) + 8 * hh) * 8; u32x4 vw = (u32x4){0u, 0u, 0u, 0u};
;           if (ok) vw = vwp[hh];
; #pragma unroll
.Lgq_nopf:
	ds_write_b128 v0, v[38:41] offset:16384
	ds_write_b128 v0, v[42:45] offset:24576
	ds_write_b128 v0, v[76:79] offset:32768
	ds_write_b128 v0, v[122:125] offset:40960
	s_waitcnt lgkmcnt(0)
	s_barrier
	ds_read2st64_b64 v[38:41], v87 offset0:32 offset1:64
	v_add_u32_e32 v0, 8, v87
	s_waitcnt lgkmcnt(0)
	v_mul_f32_e32 v2, 0x3fb8aa3b, v38
	v_mul_f32_e32 v4, 0x3fb8aa3b, v39
	v_mul_f32_e32 v6, 0x3fb8aa3b, v40
	v_mul_f32_e32 v8, 0x3fb8aa3b, v41
	v_mul_f32_e32 v10, 0xbfb8aa3b, v38
	v_mul_f32_e32 v18, 0xbfb8aa3b, v39
	v_mul_f32_e32 v20, 0xbfb8aa3b, v40
	v_mul_f32_e32 v38, 0xbfb8aa3b, v41
	v_exp_f32_e32 v2, v2
	v_exp_f32_e32 v4, v4
	v_exp_f32_e32 v6, v6
	v_exp_f32_e32 v8, v8
	v_exp_f32_e32 v10, v10
	v_exp_f32_e32 v18, v18
	v_exp_f32_e32 v20, v20
	v_exp_f32_e32 v38, v38
	v_cndmask_b32_e64 v42, v126, 0, vcc
	v_cndmask_b32_e64 v46, v130, 0, vcc
	v_lshlrev_b32_e32 v48, 16, v42
	v_and_b32_e32 v42, 0xffff0000, v42
	v_lshlrev_b32_e32 v50, 16, v46
	v_and_b32_e32 v46, 0xffff0000, v46
	v_mul_f32_e32 v48, 0x3e000000, v48
	v_mul_f32_e32 v42, 0x3e000000, v42
	v_cndmask_b32_e64 v39, v127, 0, vcc
	v_mul_f32_e32 v10, v10, v50
	v_mul_f32_e32 v18, v18, v46
	v_mul_f32_e32 v20, v20, v50
	v_mul_f32_e32 v46, v38, v46
	v_mul_f32_e32 v2, v48, v2
	v_mul_f32_e32 v4, v42, v4
	v_mul_f32_e32 v6, v48, v6
	v_mul_f32_e32 v8, v42, v8
	v_cvt_pk_bf16_f32 v38, v2, v4
	v_cvt_pk_bf16_f32 v42, v6, v8
	v_cvt_pk_bf16_f32 v76, v10, v18
	v_cvt_pk_bf16_f32 v122, v20, v46
	ds_read2st64_b64 v[124:127], v0 offset0:32 offset1:64
	v_and_b32_e32 v2, 0xffff0000, v39
	v_lshlrev_b32_e32 v0, 16, v39
	v_mul_f32_e32 v2, 0x3e000000, v2
	v_mul_f32_e32 v0, 0x3e000000, v0
	s_waitcnt lgkmcnt(0)
	v_mul_f32_e32 v10, 0x3fb8aa3b, v125
	v_mul_f32_e32 v8, 0x3fb8aa3b, v124
	v_exp_f32_e32 v10, v10
	v_exp_f32_e32 v8, v8
	v_cndmask_b32_e64 v43, v131, 0, vcc
	v_mul_f32_e32 v18, 0xbfb8aa3b, v124
	v_mul_f32_e32 v10, v2, v10
	v_mul_f32_e32 v8, v0, v8
	v_cvt_pk_bf16_f32 v39, v8, v10
	v_mul_f32_e32 v10, 0x3fb8aa3b, v127
	v_mul_f32_e32 v8, 0x3fb8aa3b, v126
	v_exp_f32_e32 v10, v10
	v_exp_f32_e32 v8, v8
	v_lshlrev_b32_e32 v4, 16, v43
	v_and_b32_e32 v6, 0xffff0000, v43
	v_mul_f32_e32 v2, v2, v10
	v_exp_f32_e32 v18, v18
	v_mul_f32_e32 v0, v0, v8
	v_cvt_pk_bf16_f32 v43, v0, v2
	v_mul_f32_e32 v2, 0xbfb8aa3b, v125
	v_mul_f32_e32 v8, 0xbfb8aa3b, v126
	v_exp_f32_e32 v2, v2
	v_exp_f32_e32 v8, v8
	v_mul_f32_e32 v10, 0xbfb8aa3b, v127
	v_exp_f32_e32 v10, v10
	v_mul_f32_e32 v0, v18, v4
	v_mul_f32_e32 v2, v2, v6
	v_cvt_pk_bf16_f32 v77, v0, v2
	v_mul_f32_e32 v0, v8, v4
	v_mul_f32_e32 v2, v10, v6
	v_cvt_pk_bf16_f32 v123, v0, v2
	v_add_u32_e32 v0, 16, v87
	ds_read2st64_b64 v[124:127], v0 offset0:32 offset1:64
	v_cndmask_b32_e64 v40, v128, 0, vcc
	v_and_b32_e32 v2, 0xffff0000, v40
	v_lshlrev_b32_e32 v0, 16, v40
	v_mul_f32_e32 v2, 0x3e000000, v2
	s_waitcnt lgkmcnt(0)
	v_mul_f32_e32 v10, 0x3fb8aa3b, v125
	v_mul_f32_e32 v8, 0x3fb8aa3b, v124
	v_exp_f32_e32 v10, v10
	v_exp_f32_e32 v8, v8
	v_mul_f32_e32 v0, 0x3e000000, v0
	v_cndmask_b32_e64 v44, v132, 0, vcc
	v_mul_f32_e32 v10, v2, v10
	v_mul_f32_e32 v8, v0, v8
	v_cvt_pk_bf16_f32 v40, v8, v10
	v_mul_f32_e32 v10, 0x3fb8aa3b, v127
	v_mul_f32_e32 v8, 0x3fb8aa3b, v126
	v_exp_f32_e32 v10, v10
	v_exp_f32_e32 v8, v8
	v_mul_f32_e32 v18, 0xbfb8aa3b, v124
	v_lshlrev_b32_e32 v4, 16, v44
	v_mul_f32_e32 v2, v2, v10
	v_and_b32_e32 v6, 0xffff0000, v44
	v_exp_f32_e32 v18, v18
	v_mul_f32_e32 v0, v0, v8
	v_cvt_pk_bf16_f32 v44, v0, v2
	v_mul_f32_e32 v2, 0xbfb8aa3b, v125
	v_mul_f32_e32 v8, 0xbfb8aa3b, v126
	v_exp_f32_e32 v2, v2
	v_exp_f32_e32 v8, v8
	v_mul_f32_e32 v10, 0xbfb8aa3b, v127
	v_exp_f32_e32 v10, v10
	v_mul_f32_e32 v0, v18, v4
	v_mul_f32_e32 v2, v2, v6
	v_cvt_pk_bf16_f32 v78, v0, v2
	v_mul_f32_e32 v0, v8, v4
	v_mul_f32_e32 v2, v10, v6
	v_cvt_pk_bf16_f32 v124, v0, v2
	v_add_u32_e32 v0, 24, v87
	v_cndmask_b32_e64 v41, v129, 0, vcc
	ds_read2st64_b64 v[126:129], v0 offset0:32 offset1:64
	v_and_b32_e32 v2, 0xffff0000, v41
	v_lshlrev_b32_e32 v0, 16, v41
	v_mul_f32_e32 v2, 0x3e000000, v2
	v_mul_f32_e32 v0, 0x3e000000, v0
	s_waitcnt lgkmcnt(0)
	v_mul_f32_e32 v10, 0x3fb8aa3b, v127
	v_mul_f32_e32 v8, 0x3fb8aa3b, v126
	v_exp_f32_e32 v10, v10
	v_exp_f32_e32 v8, v8
	v_cndmask_b32_e64 v45, v133, 0, vcc
	v_lshlrev_b32_e32 v4, 16, v45
	v_mul_f32_e32 v10, v2, v10
	v_mul_f32_e32 v8, v0, v8
	v_cvt_pk_bf16_f32 v41, v8, v10
	v_mul_f32_e32 v10, 0x3fb8aa3b, v129
	v_mul_f32_e32 v8, 0x3fb8aa3b, v128
	v_exp_f32_e32 v10, v10
	v_exp_f32_e32 v8, v8
	v_and_b32_e32 v6, 0xffff0000, v45
	v_mul_f32_e32 v18, 0xbfb8aa3b, v126
	v_mul_f32_e32 v2, v2, v10
	v_mul_f32_e32 v0, v0, v8
	v_cvt_pk_bf16_f32 v45, v0, v2
	v_mul_f32_e32 v2, 0xbfb8aa3b, v127
	v_exp_f32_e32 v18, v18
	v_exp_f32_e32 v2, v2
	v_mul_f32_e32 v8, 0xbfb8aa3b, v128
	v_mul_f32_e32 v10, 0xbfb8aa3b, v129
	v_exp_f32_e32 v8, v8
	v_exp_f32_e32 v10, v10
	v_mul_f32_e32 v0, v18, v4
	v_mul_f32_e32 v2, v2, v6
	v_cvt_pk_bf16_f32 v79, v0, v2
	v_mul_f32_e32 v0, v8, v4
	v_mul_f32_e32 v2, v10, v6
	v_cvt_pk_bf16_f32 v125, v0, v2
	ds_write_b128 v84, v[38:41] offset:49152
	ds_write_b128 v84, v[42:45] offset:58368
	ds_write_b128 v85, v[76:79]
	ds_write_b128 v86, v[122:125]
	v_cndmask_b32_e64 v0, v37, 0, vcc
	v_cndmask_b32_e64 v2, v36, 0, vcc
	v_cndmask_b32_e64 v4, v35, 0, vcc
	v_cndmask_b32_e64 v6, v34, 0, vcc
	v_lshl_add_u64 v[38:39], s[28:29], 0, v[64:65]
	ds_write_b16 v90, v6
	ds_write_b16_d16_hi v90, v6 offset:144
	ds_write_b16 v90, v4 offset:288
	ds_write_b16_d16_hi v90, v4 offset:432
	ds_write_b16 v90, v2 offset:576
	ds_write_b16_d16_hi v90, v2 offset:720
	ds_write_b16 v90, v0 offset:864
	ds_write_b16_d16_hi v90, v0 offset:1008
	v_cndmask_b32_e64 v0, v33, 0, vcc
	v_cndmask_b32_e64 v2, v32, 0, vcc
	v_cndmask_b32_e64 v4, v31, 0, vcc
	v_cndmask_b32_e64 v6, v30, 0, vcc
	v_add_co_u32_e32 v30, vcc, s8, v38
	v_lshl_add_u64 v[42:43], s[28:29], 0, v[62:63]
	s_nop 0
	v_addc_co_u32_e32 v31, vcc, 0, v39, vcc
	v_add_co_u32_e32 v34, vcc, s8, v42
	s_mov_b32 s8, 0x50108000
	s_nop 0
	v_addc_co_u32_e32 v35, vcc, 0, v43, vcc
	v_add_co_u32_e32 v38, vcc, s8, v38
	ds_write_b16 v90, v6 offset:9216
	ds_write_b16_d16_hi v90, v6 offset:9360
	ds_write_b16 v90, v4 offset:9504
	ds_write_b16_d16_hi v90, v4 offset:9648
	ds_write_b16 v90, v2 offset:9792
	ds_write_b16_d16_hi v90, v2 offset:9936
	ds_write_b16 v90, v0 offset:10080
	ds_write_b16_d16_hi v90, v0 offset:10224
	v_addc_co_u32_e32 v39, vcc, 0, v39, vcc
	v_add_co_u32_e32 v42, vcc, s8, v42
	s_nop 1
	v_addc_co_u32_e32 v43, vcc, 0, v43, vcc
	v_add_u32_e32 v0, v81, v82
	v_and_b32_e32 v4, 64, v225
	v_add_u32_e32 v4, 64, v4
	s_waitcnt lgkmcnt(0)
	ds_write_b128 v0, v[150:153]
	v_add_u32_e32 v0, v81, v88
	ds_write_b128 v0, v[154:157]
	v_add_u32_e32 v0, v83, v82
	ds_write_b128 v0, v[158:161]
	v_add_u32_e32 v0, v83, v88
	ds_write_b128 v0, v[162:165]
	s_waitcnt lgkmcnt(0)
	s_barrier
; #define LAS __attribute__((address_space(3)))
; __device__ __forceinline__ bf16_t f2bf(float f) { return (bf16_t)(cvt_pk_bf16(f, 0.f) & 0xffffu); }
; template <int MODE>
; __device__ __forceinline__ void gla_item(const int TID, const Params& p, int l, int ci, int head, LAS unsigned char* lds, const float (&wg)[2][16], const float (&bg)[2], const float (&ngv)[16]) {
;     ...
;     const LAS bf16_t* qe0 = (const LAS bf16_t*)(lds + GL_QE0); const LAS bf16_t* qe1 = (const LAS bf16_t*)(lds + GL_QE1); const LAS bf16_t* ke0 = (const LAS bf16_t*)(lds + GL_KE0); const LAS bf16_t* ke1 = (const LAS bf16_t*)(lds + GL_KE1);
;     LAS bf16_t* att = (LAS bf16_t*)(lds + GL_ATT);
;     { const int it = wid >> 1;
; #pragma unroll
;       for (int t2 = 0; t2 < 2; ++t2) { const int jt = (wid & 1) * 2 + t2; f32x4 af = (f32x4){0.f, 0.f, 0.f, 0.f}, ab = af;
;           af = mma_lds(af, qe0 + it * 16 * GLD, ke0 + jt * 16 * GLD, GLD, 2, lane); ab = mma_lds(ab, qe1 + it * 16 * GLD, ke1 + jt * 16 * GLD, GLD, 2, lane);
; #pragma unroll
;           for (int j = 0; j < 4; ++j) { const int i_ = it * 16 + (lane >> 4) * 4 + j, j_ = jt * 16 + (lane & 15); att[i_ * GLD + j_] = f2bf((j_ <= i_ ? af[j] : 0.f) + (j_ >= i_ ? ab[j] : 0.f)); } } }
;     __syncthreads();
;     LAS float* os = (LAS float*)(lds + GL_OS);
;     { const int it = wid >> 1; const LAS bf16_t* sp0 = (const LAS bf16_t*)(lds + GL_SP0); const LAS bf16_t* sp1 = (const LAS bf16_t*)(lds + GL_SP1);
; #pragma unroll
;       for (int t4 = 0; t4 < 4; ++t4) { const int vt = (wid & 1) * 4 + t4; f32x4 acc = (f32x4){0.f, 0.f, 0.f, 0.f};
;           acc = mma_lds_sw(acc, att + it * 16 * GLD, -1, vT + vt * 16 * GLD, vt * 16, GLD, 2, lane); acc = mma_lds(acc, qe0 + it * 16 * GLD, sp0 + vt * 16 * GLD, GLD, 2, lane); acc = mma_lds(acc, qe1 + it * 16 * GLD, sp1 + vt * 16 * GLD, GLD, 2, lane);
; #pragma unroll
;           for (int j = 0; j < 4; ++j) os[(it * 16 + (lane >> 4) * 4 + j) * 132 + vt * 16 + (lane & 15)] = acc[j]; } }
	ds_read_b128 v[30:33], v89 offset:49152
	ds_read_b128 v[34:37], v89 offset:49216
	ds_read_b128 v[38:41], v91
	ds_read_b128 v[42:45], v91 offset:64
	s_waitcnt lgkmcnt(1)
	v_mfma_f32_16x16x32_bf16 v[30:33], v[30:33], v[38:41], 0
	ds_read_b128 v[38:41], v89 offset:58368
	s_waitcnt lgkmcnt(1)
	v_mfma_f32_16x16x32_bf16 v[30:33], v[34:37], v[42:45], v[30:33]
	ds_read_b128 v[34:37], v89 offset:58432
	ds_read_b128 v[42:45], v92
	ds_read_b128 v[76:79], v92 offset:64
	s_waitcnt lgkmcnt(1)
	v_mfma_f32_16x16x32_bf16 v[38:41], v[38:41], v[42:45], 0
	s_nop 2
	v_cndmask_b32_e64 v0, v30, 0, s[38:39]
	s_waitcnt lgkmcnt(0)
	v_mfma_f32_16x16x32_bf16 v[34:37], v[34:37], v[76:79], v[38:41]
	s_nop 7
	v_cndmask_b32_e64 v2, v34, 0, s[40:41]
	v_add_f32_e32 v0, v0, v2
	v_cvt_pk_bf16_f32 v0, v0, v183
	ds_write_b16 v106, v0
	v_cndmask_b32_e64 v0, v31, 0, s[42:43]
	v_cndmask_b32_e64 v2, 0, v35, s[38:39]
	v_add_f32_e32 v0, v0, v2
	v_cvt_pk_bf16_f32 v0, v0, v183
	ds_write_b16 v106, v0 offset:144
	v_cndmask_b32_e64 v0, v32, 0, s[44:45]
	v_cndmask_b32_e64 v2, v36, 0, s[46:47]
	v_add_f32_e32 v0, v0, v2
	v_cvt_pk_bf16_f32 v0, v0, v183
	ds_write_b16 v106, v0 offset:288
	v_cndmask_b32_e64 v0, v33, 0, s[48:49]
	v_cndmask_b32_e64 v2, v37, 0, s[50:51]
	v_add_f32_e32 v0, v0, v2
	v_cvt_pk_bf16_f32 v0, v0, v183
	ds_write_b16 v106, v0 offset:432
	ds_read_b128 v[30:33], v89 offset:49152
	ds_read_b128 v[34:37], v89 offset:49216
	ds_read_b128 v[38:41], v93
	ds_read_b128 v[42:45], v93 offset:64
	s_waitcnt lgkmcnt(1)
	v_mfma_f32_16x16x32_bf16 v[30:33], v[30:33], v[38:41], 0
	ds_read_b128 v[38:41], v89 offset:58368
	s_waitcnt lgkmcnt(1)
	v_mfma_f32_16x16x32_bf16 v[30:33], v[34:37], v[42:45], v[30:33]
	ds_read_b128 v[34:37], v89 offset:58432
	ds_read_b128 v[42:45], v94
	ds_read_b128 v[76:79], v94 offset:64
	s_waitcnt lgkmcnt(1)
	v_mfma_f32_16x16x32_bf16 v[38:41], v[38:41], v[42:45], 0
	s_nop 2
	v_cndmask_b32_e64 v0, v30, 0, s[52:53]
	s_waitcnt lgkmcnt(0)
	v_mfma_f32_16x16x32_bf16 v[34:37], v[34:37], v[76:79], v[38:41]
	s_nop 7
	v_cndmask_b32_e64 v2, v34, 0, s[54:55]
	v_add_f32_e32 v0, v0, v2
	v_cvt_pk_bf16_f32 v0, v0, v183
	ds_write_b16 v107, v0
	v_cndmask_b32_e64 v0, v31, 0, s[56:57]
	v_cndmask_b32_e64 v2, 0, v35, s[52:53]
	v_add_f32_e32 v0, v0, v2
	v_cvt_pk_bf16_f32 v0, v0, v183
	ds_write_b16 v107, v0 offset:144
	v_cndmask_b32_e64 v0, v32, 0, s[58:59]
	v_cndmask_b32_e64 v2, v36, 0, s[60:61]
	v_add_f32_e32 v0, v0, v2
	v_cvt_pk_bf16_f32 v0, v0, v183
	ds_write_b16 v107, v0 offset:288
	v_cndmask_b32_e64 v0, v33, 0, s[62:63]
	v_cndmask_b32_e64 v2, v37, 0, s[64:65]
	v_add_f32_e32 v0, v0, v2
	v_cvt_pk_bf16_f32 v0, v0, v183
	ds_write_b16 v107, v0 offset:432
	s_waitcnt lgkmcnt(0)
	s_barrier
	ds_read_b128 v[30:33], v108
	ds_read_b128 v[34:37], v109
	ds_read_b128 v[38:41], v110
	s_waitcnt lgkmcnt(1)
	v_mfma_f32_16x16x32_bf16 v[30:33], v[30:33], v[34:37], 0
	ds_read_b128 v[34:37], v111
	ds_read_b128 v[42:45], v89 offset:49152
	v_add_u32_e32 v0, v97, v98
	v_xor_b32_e32 v2, 1, v225
	s_waitcnt lgkmcnt(1)
	v_mfma_f32_16x16x32_bf16 v[30:33], v[38:41], v[34:37], v[30:33]
	ds_read_b128 v[34:37], v89 offset:49216
	ds_read_b128 v[38:41], v95
	ds_read_b128 v[76:79], v95 offset:64
	v_cmp_lt_i32_e32 vcc, v2, v4
	s_waitcnt lgkmcnt(1)
	v_mfma_f32_16x16x32_bf16 v[30:33], v[42:45], v[38:41], v[30:33]
	ds_read_b128 v[38:41], v89 offset:58368
	v_cndmask_b32_e32 v2, v225, v2, vcc
	v_lshlrev_b32_e32 v2, 2, v2
	s_waitcnt lgkmcnt(1)
	v_mfma_f32_16x16x32_bf16 v[30:33], v[34:37], v[76:79], v[30:33]
	ds_read_b128 v[34:37], v89 offset:58432
	ds_read_b128 v[42:45], v96
	ds_read_b128 v[76:79], v96 offset:64
	s_waitcnt lgkmcnt(1)
	v_mfma_f32_16x16x32_bf16 v[30:33], v[38:41], v[42:45], v[30:33]
	s_waitcnt lgkmcnt(0)
	v_mfma_f32_16x16x32_bf16 v[30:33], v[34:37], v[76:79], v[30:33]
	s_nop 7
	ds_write2_b32 v0, v30, v31 offset1:132
	v_add_u32_e32 v0, 0x400, v0
	ds_write2_b32 v0, v32, v33 offset0:8 offset1:140
	ds_read_b128 v[30:33], v108
	ds_read_b128 v[34:37], v110
	ds_read_b128 v[38:41], v112
	ds_read_b128 v[42:45], v113
	s_waitcnt lgkmcnt(1)
	v_mfma_f32_16x16x32_bf16 v[30:33], v[30:33], v[38:41], 0
	ds_read_b128 v[38:41], v89 offset:49152
	v_add_u32_e32 v0, 0x400, v114
	s_waitcnt lgkmcnt(1)
	v_mfma_f32_16x16x32_bf16 v[30:33], v[34:37], v[42:45], v[30:33]
	ds_read_b128 v[34:37], v89 offset:49216
	ds_read_b128 v[42:45], v99
	ds_read_b128 v[76:79], v99 offset:64
	s_waitcnt lgkmcnt(1)
	v_mfma_f32_16x16x32_bf16 v[30:33], v[38:41], v[42:45], v[30:33]
	ds_read_b128 v[38:41], v89 offset:58368
	s_waitcnt lgkmcnt(1)
	v_mfma_f32_16x16x32_bf16 v[30:33], v[34:37], v[76:79], v[30:33]
	ds_read_b128 v[34:37], v89 offset:58432
	ds_read_b128 v[42:45], v100
	ds_read_b128 v[76:79], v100 offset:64
	s_waitcnt lgkmcnt(1)
	v_mfma_f32_16x16x32_bf16 v[30:33], v[38:41], v[42:45], v[30:33]
	s_waitcnt lgkmcnt(0)
	v_mfma_f32_16x16x32_bf16 v[30:33], v[34:37], v[76:79], v[30:33]
	s_nop 7
	ds_write2_b32 v114, v30, v31 offset1:132
	ds_write2_b32 v0, v32, v33 offset0:8 offset1:140
	ds_read_b128 v[30:33], v108
	ds_read_b128 v[34:37], v110
	ds_read_b128 v[38:41], v115
	ds_read_b128 v[42:45], v116
	s_waitcnt lgkmcnt(1)
	v_mfma_f32_16x16x32_bf16 v[30:33], v[30:33], v[38:41], 0
	ds_read_b128 v[38:41], v89 offset:49152
	v_add_u32_e32 v0, 0x400, v117
	s_waitcnt lgkmcnt(1)
	v_mfma_f32_16x16x32_bf16 v[30:33], v[34:37], v[42:45], v[30:33]
	ds_read_b128 v[34:37], v89 offset:49216
	ds_read_b128 v[42:45], v101
	ds_read_b128 v[76:79], v101 offset:64
	s_waitcnt lgkmcnt(1)
	v_mfma_f32_16x16x32_bf16 v[30:33], v[38:41], v[42:45], v[30:33]
	ds_read_b128 v[38:41], v89 offset:58368
	s_waitcnt lgkmcnt(1)
; template <int MODE>
; __device__ __forceinline__ void gla_item(const int TID, const Params& p, int l, int ci, int head, LAS unsigned char* lds, const float (&wg)[2][16], const float (&bg)[2], const float (&ngv)[16]) {
;     ...
;           acc = mma_lds_sw(acc, att + it * 16 * GLD, -1, vT + vt * 16 * GLD, vt * 16, GLD, 2, lane); acc = mma_lds(acc, qe0 + it * 16 * GLD, sp0 + vt * 16 * GLD, GLD, 2, lane); acc = mma_lds(acc, qe1 + it * 16 * GLD, sp1 + vt * 16 * GLD, GLD, 2, lane);
; #pragma unroll
;           for (int j = 0; j < 4; ++j) os[(it * 16 + (lane >> 4) * 4 + j) * 132 + vt * 16 + (lane & 15)] = acc[j]; } }
;     __syncthreads();
;     { const int r = tid >> 3, v0 = (tid & 7) * 16; float o[16]; float ss = 0.f;
; #pragma unroll
;       for (int i = 0; i < 16; ++i) { o[i] = os[r * 132 + v0 + i]; ss += o[i] * o[i]; }
;       ss += __shfl_xor(ss, 1); ss += __shfl_xor(ss, 2); ss += __shfl_xor(ss, 4);
;       const float rs = rsqrtf(ss * (1.0f / 128.0f) + 1e-6f);
	v_mfma_f32_16x16x32_bf16 v[30:33], v[34:37], v[76:79], v[30:33]
	ds_read_b128 v[34:37], v89 offset:58432
	ds_read_b128 v[42:45], v102
	ds_read_b128 v[76:79], v102 offset:64
	s_waitcnt lgkmcnt(1)
	v_mfma_f32_16x16x32_bf16 v[30:33], v[38:41], v[42:45], v[30:33]
	s_waitcnt lgkmcnt(0)
	v_mfma_f32_16x16x32_bf16 v[30:33], v[34:37], v[76:79], v[30:33]
	s_nop 7
	ds_write2_b32 v117, v30, v31 offset1:132
	ds_write2_b32 v0, v32, v33 offset0:8 offset1:140
	ds_read_b128 v[30:33], v108
	ds_read_b128 v[34:37], v110
	ds_read_b128 v[38:41], v118
	ds_read_b128 v[42:45], v119
	s_waitcnt lgkmcnt(1)
	v_mfma_f32_16x16x32_bf16 v[30:33], v[30:33], v[38:41], 0
	ds_read_b128 v[38:41], v89 offset:49152
	v_add_u32_e32 v0, 0x400, v120
	s_waitcnt lgkmcnt(1)
	v_mfma_f32_16x16x32_bf16 v[30:33], v[34:37], v[42:45], v[30:33]
	ds_read_b128 v[34:37], v89 offset:49216
	ds_read_b128 v[42:45], v103
	ds_read_b128 v[76:79], v103 offset:64
	s_waitcnt lgkmcnt(1)
	v_mfma_f32_16x16x32_bf16 v[30:33], v[38:41], v[42:45], v[30:33]
	ds_read_b128 v[38:41], v89 offset:58368
	s_waitcnt lgkmcnt(1)
	v_mfma_f32_16x16x32_bf16 v[30:33], v[34:37], v[76:79], v[30:33]
	ds_read_b128 v[34:37], v89 offset:58432
	ds_read_b128 v[42:45], v104
	ds_read_b128 v[76:79], v104 offset:64
	s_waitcnt lgkmcnt(1)
	v_mfma_f32_16x16x32_bf16 v[30:33], v[38:41], v[42:45], v[30:33]
	s_waitcnt lgkmcnt(0)
	v_mfma_f32_16x16x32_bf16 v[30:33], v[34:37], v[76:79], v[30:33]
	s_nop 7
	ds_write2_b32 v120, v30, v31 offset1:132
	ds_write2_b32 v0, v32, v33 offset0:8 offset1:140
	s_waitcnt vmcnt(0) lgkmcnt(0)
	s_barrier
	ds_read_b128 v[42:45], v105
	ds_read_b128 v[38:41], v105 offset:16
	ds_read_b128 v[34:37], v105 offset:32
	ds_read_b128 v[30:33], v105 offset:48
	s_waitcnt lgkmcnt(3)
	v_mul_f32_e32 v0, v43, v43
	v_fmac_f32_e32 v0, v42, v42
	v_fmac_f32_e32 v0, v44, v44
	v_fmac_f32_e32 v0, v45, v45
	s_waitcnt lgkmcnt(2)
	v_fmac_f32_e32 v0, v38, v38
	v_fmac_f32_e32 v0, v39, v39
	v_fmac_f32_e32 v0, v40, v40
	v_fmac_f32_e32 v0, v41, v41
	s_waitcnt lgkmcnt(1)
	v_fmac_f32_e32 v0, v34, v34
	v_fmac_f32_e32 v0, v35, v35
	v_fmac_f32_e32 v0, v36, v36
	v_fmac_f32_e32 v0, v37, v37
	s_waitcnt lgkmcnt(0)
	v_fmac_f32_e32 v0, v30, v30
	v_fmac_f32_e32 v0, v31, v31
	v_fmac_f32_e32 v0, v32, v32
	v_fmac_f32_e32 v0, v33, v33
	ds_bpermute_b32 v2, v2, v0
	s_waitcnt lgkmcnt(0)
	v_add_f32_e32 v0, v0, v2
	v_xor_b32_e32 v2, 2, v225
	v_cmp_lt_i32_e32 vcc, v2, v4
	s_nop 1
	v_cndmask_b32_e32 v2, v225, v2, vcc
	v_lshlrev_b32_e32 v2, 2, v2
	ds_bpermute_b32 v2, v2, v0
	s_waitcnt lgkmcnt(0)
	v_add_f32_e32 v0, v0, v2
	v_xor_b32_e32 v2, 4, v225
	v_cmp_lt_i32_e32 vcc, v2, v4
	s_nop 1
	v_cndmask_b32_e32 v2, v225, v2, vcc
	v_lshlrev_b32_e32 v2, 2, v2
	ds_bpermute_b32 v2, v2, v0
	v_cmp_le_i32_e32 vcc, s21, v13
	s_and_saveexec_b64 s[66:67], vcc
	s_cbranch_execz .LBB0_334
; __device__ __forceinline__ unsigned cvt_pk_bf16(float lo, float hi) { unsigned r; asm volatile("v_cvt_pk_bf16_f32 %0, %1, %2" : "=v"(r) : "v"(lo), "v"(hi)); return r; }
; __device__ __forceinline__ float bflo(unsigned w) { return __uint_as_float(w << 16); }
; __device__ __forceinline__ float bfhi(unsigned w) { return __uint_as_float(w & 0xffff0000u); }
; __device__ __forceinline__ float silu(float x) { return x * sigm(x); }
; template <int MODE>
; __device__ __forceinline__ void gla_item(const int TID, const Params& p, int l, int ci, int head, LAS unsigned char* lds, const float (&wg)[2][16], const float (&bg)[2], const float (&ngv)[16]) {
;     ...
;       if (r >= rmin) { const size_t tok = (size_t)(tok0 + r); bf16_t* yall = (bf16_t*)(p.ws + WS_YALL);
; #pragma unroll
;           for (int hh = 0; hh < 2; ++hh) { const u32x4 gw = gwp[hh]; u32x4 w;
; #pragma unroll
;               for (int i = 0; i < 4; ++i) { const int e = hh * 8 + 2 * i; w[i] = cvt_pk_bf16(o[e] * rs * ngv[e] * silu(bflo(gw[i])), o[e + 1] * rs * ngv[e + 1] * silu(bfhi(gw[i]))); }
;               *(u32x4*)(yall + tok * D + 512 + head * 128 + v0 + hh * 8) = w; } } }
	s_waitcnt lgkmcnt(0)
	v_add_f32_e32 v0, v0, v2
	v_fmamk_f32 v0, v0, 0x3c000000, v226
	v_cmp_gt_f32_e32 vcc, s19, v0
	v_mul_f32_e32 v2, 0x4b800000, v0
	v_lshlrev_b32_e32 v46, 16, v26
	v_cndmask_b32_e32 v0, v0, v2, vcc
	v_rsq_f32_e32 v0, v0
	v_lshlrev_b32_e32 v48, 16, v27
	v_lshlrev_b32_e32 v50, 16, v28
	v_lshlrev_b32_e32 v52, 16, v29
	v_mul_f32_e32 v2, 0x45800000, v0
	v_cndmask_b32_e32 v20, v0, v2, vcc
	v_mul_f32_e32 v0, 0xbfb8aa3b, v46
	v_exp_f32_e32 v0, v0
	v_mul_f32_e32 v123, v42, v20
	v_mul_f32_e32 v43, v43, v20
	v_mul_f32_e32 v39, v39, v20
	v_add_f32_e32 v0, 1.0, v0
	v_rcp_f32_e32 v122, v0
	v_and_b32_e32 v0, 0xffff0000, v26
	v_mul_f32_e32 v4, 0xbfb8aa3b, v0
	v_exp_f32_e32 v4, v4
	v_pk_mul_f32 v[122:123], v[122:123], v[46:47]
	v_and_b32_e32 v6, 0xffff0000, v29
	v_mul_f32_e32 v2, v122, v123
	v_add_f32_e32 v4, 1.0, v4
	v_rcp_f32_e32 v42, v4
	v_add_u32_e32 v76, s1, v13
	v_ashrrev_i32_e32 v77, 31, v76
	v_lshlrev_b32_e32 v54, 16, v22
	v_pk_mul_f32 v[42:43], v[42:43], v[0:1]
	v_lshlrev_b64 v[76:77], 12, v[76:77]
	v_mul_f32_e32 v0, v42, v43
	v_cvt_pk_bf16_f32 v26, v2, v0
	v_mul_f32_e32 v0, 0xbfb8aa3b, v48
	v_exp_f32_e32 v0, v0
	v_and_b32_e32 v2, 0xffff0000, v27
	v_mul_f32_e32 v4, 0xbfb8aa3b, v2
	v_exp_f32_e32 v4, v4
	v_add_f32_e32 v0, 1.0, v0
	v_rcp_f32_e32 v42, v0
	v_mul_f32_e32 v43, v44, v20
	v_add_f32_e32 v4, 1.0, v4
	v_lshl_add_u64 v[76:77], s[94:95], 0, v[76:77]
	v_pk_mul_f32 v[42:43], v[42:43], v[48:49]
	s_lshl_b32 s24, s24, 1
	v_mul_f32_e32 v0, v42, v43
	v_rcp_f32_e32 v42, v4
	v_mul_f32_e32 v43, v45, v20
	v_and_b32_e32 v4, 0xffff0000, v28
	v_lshl_add_u64 v[76:77], v[76:77], 0, s[24:25]
	v_pk_mul_f32 v[42:43], v[42:43], v[2:3]
	v_lshl_add_u64 v[78:79], v[76:77], 0, v[182:183]
	v_mul_f32_e32 v2, v42, v43
	v_cvt_pk_bf16_f32 v27, v0, v2
	v_mul_f32_e32 v0, 0xbfb8aa3b, v50
	v_exp_f32_e32 v0, v0
	v_mul_f32_e32 v2, 0xbfb8aa3b, v4
	v_exp_f32_e32 v2, v2
	v_mul_f32_e32 v43, v38, v20
	v_add_f32_e32 v0, 1.0, v0
	v_rcp_f32_e32 v42, v0
	v_add_f32_e32 v2, 1.0, v2
	v_rcp_f32_e32 v38, v2
	s_mov_b32 s1, 0x32c60000
	v_pk_mul_f32 v[42:43], v[42:43], v[50:51]
	v_and_b32_e32 v8, 0xffff0000, v22
	v_mul_f32_e32 v0, v42, v43
	v_pk_mul_f32 v[38:39], v[38:39], v[4:5]
	v_lshlrev_b32_e32 v56, 16, v23
	v_mul_f32_e32 v2, v38, v39
	v_cvt_pk_bf16_f32 v28, v0, v2
	v_mul_f32_e32 v0, 0xbfb8aa3b, v52
	v_exp_f32_e32 v0, v0
	v_mul_f32_e32 v2, 0xbfb8aa3b, v6
	v_exp_f32_e32 v2, v2
	v_mul_f32_e32 v39, v40, v20
	v_add_f32_e32 v0, 1.0, v0
	v_rcp_f32_e32 v38, v0
	v_add_f32_e32 v2, 1.0, v2
	v_and_b32_e32 v10, 0xffff0000, v23
	v_lshlrev_b32_e32 v58, 16, v24
	v_pk_mul_f32 v[38:39], v[38:39], v[52:53]
	v_and_b32_e32 v18, 0xffff0000, v24
	v_mul_f32_e32 v0, v38, v39
	v_rcp_f32_e32 v38, v2
	v_mul_f32_e32 v39, v41, v20
	v_lshlrev_b32_e32 v60, 16, v25
	s_mov_b64 s[8:9], 0x32c60400
	v_pk_mul_f32 v[38:39], v[38:39], v[6:7]
	v_lshl_add_u64 v[76:77], v[78:79], 0, s[8:9]
	v_mul_f32_e32 v2, v38, v39
	v_cvt_pk_bf16_f32 v29, v0, v2
	v_mul_f32_e32 v0, 0xbfb8aa3b, v54
	v_exp_f32_e32 v0, v0
	v_add_co_u32_e32 v38, vcc, s1, v78
	v_mul_f32_e32 v2, 0xbfb8aa3b, v8
	s_nop 0
	v_addc_co_u32_e32 v39, vcc, 0, v79, vcc
	v_add_f32_e32 v0, 1.0, v0
	flat_store_dwordx4 v[38:39], v[26:29] offset:1024
	v_exp_f32_e32 v2, v2
	s_nop 0
	v_rcp_f32_e32 v26, v0
	v_mul_f32_e32 v27, v34, v20
	v_add_f32_e32 v2, 1.0, v2
	v_pk_mul_f32 v[26:27], v[26:27], v[54:55]
	s_nop 0
	v_mul_f32_e32 v0, v26, v27
	v_rcp_f32_e32 v26, v2
	v_mul_f32_e32 v27, v35, v20
	v_pk_mul_f32 v[26:27], v[26:27], v[8:9]
	s_nop 0
	v_mul_f32_e32 v2, v26, v27
	v_cvt_pk_bf16_f32 v22, v0, v2
	v_mul_f32_e32 v0, 0xbfb8aa3b, v56
	v_exp_f32_e32 v0, v0
	v_mul_f32_e32 v2, 0xbfb8aa3b, v10
	v_exp_f32_e32 v2, v2
	v_mul_f32_e32 v27, v36, v20
	v_add_f32_e32 v0, 1.0, v0
	v_rcp_f32_e32 v26, v0
	v_add_f32_e32 v2, 1.0, v2
	v_pk_mul_f32 v[26:27], v[26:27], v[56:57]
	s_nop 0
	v_mul_f32_e32 v0, v26, v27
	v_rcp_f32_e32 v26, v2
	v_mul_f32_e32 v27, v37, v20
	v_pk_mul_f32 v[26:27], v[26:27], v[10:11]
	s_nop 0
	v_mul_f32_e32 v2, v26, v27
	v_cvt_pk_bf16_f32 v23, v0, v2
	v_mul_f32_e32 v0, 0xbfb8aa3b, v58
	v_exp_f32_e32 v0, v0
	v_mul_f32_e32 v2, 0xbfb8aa3b, v18
	v_exp_f32_e32 v2, v2
	v_mul_f32_e32 v27, v30, v20
	v_add_f32_e32 v0, 1.0, v0
	v_rcp_f32_e32 v26, v0
	v_add_f32_e32 v2, 1.0, v2
	v_pk_mul_f32 v[26:27], v[26:27], v[58:59]
	s_nop 0
	v_mul_f32_e32 v0, v26, v27
	v_rcp_f32_e32 v26, v2
	v_mul_f32_e32 v27, v31, v20
	v_pk_mul_f32 v[26:27], v[26:27], v[18:19]
	s_nop 0
	v_mul_f32_e32 v2, v26, v27
	v_cvt_pk_bf16_f32 v24, v0, v2
	v_mul_f32_e32 v0, 0xbfb8aa3b, v60
	v_exp_f32_e32 v0, v0
	v_mul_f32_e32 v27, v32, v20
	v_add_f32_e32 v0, 1.0, v0
	v_rcp_f32_e32 v26, v0
	s_nop 0
	v_pk_mul_f32 v[26:27], v[26:27], v[60:61]
	s_nop 0
	v_mul_f32_e32 v0, v26, v27
	v_mul_f32_e32 v27, v33, v20
	v_and_b32_e32 v20, 0xffff0000, v25
	v_mul_f32_e32 v2, 0xbfb8aa3b, v20
	v_exp_f32_e32 v2, v2
	s_nop 0
	v_add_f32_e32 v2, 1.0, v2
	v_rcp_f32_e32 v26, v2
	s_nop 0
	v_pk_mul_f32 v[26:27], v[26:27], v[20:21]
	s_nop 0
	v_mul_f32_e32 v2, v26, v27
	v_cvt_pk_bf16_f32 v25, v0, v2
	flat_store_dwordx4 v[76:77], v[22:25] offset:16
	s_branch .LBB0_334

; __device__ __forceinline__ float bflo(unsigned w) { return __uint_as_float(w << 16); }
; __device__ __forceinline__ float bfhi(unsigned w) { return __uint_as_float(w & 0xffff0000u); }
; template <int MODE>
; __device__ __forceinline__ void gla_item(const int TID, const Params& p, int l, int ci, int head, LAS unsigned char* lds, const float (&wg)[2][16], const float (&bg)[2], const float (&ngv)[16]) {
;     ...
;     { const int r = tid >> 3, k8 = (tid & 7) * 8; const int rc = r >= rmin ? r : rmin; const bf16_t* rowp = cols + (size_t)(tok0 + rc) * NINP;
;       kw = *(const u32x4*)(rowp + C_K + head * 64 + k8); if (MODE == 1) qw = *(const u32x4*)(rowp + C_Q + head * 64 + k8);
; #pragma unroll
;       for (int hh = 0; hh < 2; ++hh) { vwp[hh] = *(const u32x4*)(rowp + C_V + head * 128 + ((tid & 7) + 8 * hh) * 8); if (MODE == 1) gwp[hh] = *(const u32x4*)(rowp + C_GB + head * 128 + (tid & 7) * 16 + hh * 8); } }
;     if (MODE == 0) {
;     { const int r = tid >> 3, j4 = (tid & 7) * 4; f32x4 v = (f32x4){0.f, 0.f, 0.f, 0.f};
;       { const int rc = r >= rmin ? r : rmin; const u32x2 w = *(const u32x2*)(cols + (size_t)(tok0 + rc) * NINP + C_GLR + j4); if (r >= rmin) { v[0] = bflo(w.x); v[1] = bfhi(w.x); v[2] = bflo(w.y); v[3] = bfhi(w.y); } }
; __global__ void __launch_bounds__(512) fwd_megakernel(Params p_in) {
;     ...
;                 { const int head_ = ((b + 128) % G) & 3, kk_ = TID & 63; float wg_[2][16], bg_[2];
;                   _Pragma("unroll") for (int d = 0; d < 2; ++d) { bg_[d] = p.in[16][(l * 2 + d) * 256 + head_ * 64 + kk_]; _Pragma("unroll") for (int j = 0; j < 16; ++j) wg_[d][j] = p.in[15][((size_t)(l * 2 + d) * 16 + j) * 256 + head_ * 64 + kk_]; }
;                   float ng_[16]; _Pragma("unroll") for (int e = 0; e < 16; ++e) ng_[e] = p.in[17][l * 512 + head_ * 128 + (TID & 7) * 16 + e];
;                   for (int it = (b + 128) % G; it < NCK * 4; it += G) gla_item<0>(TID, p, l, it >> 2, it & 3, lds, wg_, bg_, ng_); }
.LBB0_737:
	s_add_i32 s0, s22, 0x80
	s_ashr_i32 s1, s0, 31
	s_abs_i32 s0, s0
	v_readlane_b32 s2, v253, 38
	s_mul_hi_u32 s2, s0, s2
	v_readlane_b32 s3, v253, 37
	s_mul_i32 s2, s2, s3
	s_sub_i32 s0, s0, s2
	s_sub_i32 s2, s0, s3
	s_cmp_ge_u32 s0, s3
	s_cselect_b32 s0, s2, s0
	s_sub_i32 s2, s0, s3
	s_cmp_ge_u32 s0, s3
	s_cselect_b32 s0, s2, s0
	s_xor_b32 s0, s0, s1
	s_sub_i32 s2, s0, s1
	v_and_b32_e32 v115, 0x7f, v194
	v_and_b32_e32 v112, 63, v194
	s_cmpk_gt_i32 s2, 0x627
	v_ashrrev_i32_e32 v114, 3, v194
	v_lshl_add_u32 v113, v115, 2, 0
	s_waitcnt vmcnt(0) lgkmcnt(0)
	s_barrier
	s_cbranch_scc1 .LBB0_798
	s_lshl_b32 s0, s2, 6
	s_and_b32 s3, s0, 0xc0
	v_readlane_b32 s40, v254, 16
	s_lshl_b32 s0, s3, 2
	v_readlane_b32 s54, v254, 30
	v_readlane_b32 s55, v254, 31
	s_add_u32 s0, s54, s0
	v_readlane_b32 s41, v254, 17
	v_readlane_b32 s42, v254, 18
	v_readlane_b32 s43, v254, 19
	v_readlane_b32 s44, v254, 20
	v_readlane_b32 s45, v254, 21
	v_readlane_b32 s46, v254, 22
	v_readlane_b32 s47, v254, 23
	v_readlane_b32 s48, v254, 24
	v_readlane_b32 s49, v254, 25
	v_readlane_b32 s50, v254, 26
	v_readlane_b32 s51, v254, 27
	v_readlane_b32 s52, v254, 28
	v_readlane_b32 s53, v254, 29
	s_addc_u32 s1, s55, 0
	v_lshlrev_b32_e32 v182, 2, v112
	v_or_b32_e32 v2, s20, v112
	v_lshl_add_u64 v[0:1], s[0:1], 0, v[182:183]
	v_or_b32_e32 v2, s3, v2
	v_readlane_b32 s40, v254, 32
	v_readlane_b32 s0, v254, 61
	v_ashrrev_i32_e32 v3, 31, v2
	v_readlane_b32 s41, v254, 33
	v_readlane_b32 s1, v254, 62
	s_mov_b32 s10, s0
	s_ashr_i32 s11, s0, 31
	v_lshl_add_u64 v[2:3], v[2:3], 2, s[40:41]
	s_lshl_b64 s[0:1], s[10:11], 14
	global_load_dword v116, v[2:3], off
	v_lshl_add_u64 v[2:3], v[0:1], 0, s[0:1]
	s_mov_b32 s0, s10
	v_readlane_b32 s42, v254, 34
	v_readlane_b32 s43, v254, 35
	v_readlane_b32 s44, v254, 36
	v_readlane_b32 s45, v254, 37
	v_readlane_b32 s46, v254, 38
	v_readlane_b32 s47, v254, 39
	v_readlane_b32 s48, v254, 40
	v_readlane_b32 s49, v254, 41
	v_readlane_b32 s50, v254, 42
	v_readlane_b32 s51, v254, 43
	v_readlane_b32 s52, v254, 44
	v_readlane_b32 s53, v254, 45
	v_readlane_b32 s54, v254, 46
	v_readlane_b32 s55, v254, 47
	s_movk_i32 s9, 0x1000
	v_writelane_b32 v254, s0, 61
	v_add_co_u32_e32 v4, vcc, s9, v2
	s_nop 0
	v_writelane_b32 v254, s1, 62
	s_or_b32 s0, s10, 1
	v_addc_co_u32_e32 v5, vcc, 0, v3, vcc
	global_load_dword v117, v[2:3], off
	global_load_dword v118, v[2:3], off offset:1024
	global_load_dword v119, v[2:3], off offset:2048
	global_load_dword v120, v[2:3], off offset:3072
	global_load_dword v121, v[4:5], off offset:1024
	global_load_dword v30, v[4:5], off offset:2048
	global_load_dword v31, v[4:5], off offset:3072
	v_lshl_or_b32 v4, s0, 8, v112
	s_movk_i32 s8, 0x2000
	v_or_b32_e32 v4, s3, v4
	s_ashr_i32 s1, s0, 31
	v_add_co_u32_e32 v6, vcc, s8, v2
	v_ashrrev_i32_e32 v5, 31, v4
	s_lshl_b64 s[0:1], s[0:1], 14
	v_addc_co_u32_e32 v7, vcc, 0, v3, vcc
	v_lshl_add_u64 v[4:5], v[4:5], 2, s[40:41]
	v_lshl_add_u64 v[0:1], v[0:1], 0, s[0:1]
	global_load_dword v122, v[4:5], off
	v_add_co_u32_e32 v4, vcc, s9, v0
	s_movk_i32 s0, 0x3000
	s_nop 0
	v_addc_co_u32_e32 v5, vcc, 0, v1, vcc
	v_add_co_u32_e32 v8, vcc, s8, v0
	v_ashrrev_i32_e32 v50, 6, v194
	s_nop 0
	v_addc_co_u32_e32 v9, vcc, 0, v1, vcc
	v_add_co_u32_e32 v10, vcc, s0, v0
	s_add_u32 s28, s94, 0x12300000
	s_nop 0
	v_addc_co_u32_e32 v11, vcc, 0, v1, vcc
	v_add_co_u32_e32 v2, vcc, s0, v2
	v_bitop3_b32 v12, v50, v194, 7 bitop3:0x78
	s_nop 0
	v_addc_co_u32_e32 v3, vcc, 0, v3, vcc
	global_load_dword v123, v[6:7], off offset:-4096
	global_load_dword v33, v[10:11], off offset:3072
	global_load_dword v35, v[2:3], off offset:3072
	global_load_dword v34, v[2:3], off offset:2048
	global_load_dword v37, v[2:3], off offset:1024
	global_load_dword v36, v[2:3], off
	global_load_dword v32, v[10:11], off offset:2048
	global_load_dword v39, v[10:11], off offset:1024
	global_load_dword v124, v[0:1], off
	global_load_dword v125, v[0:1], off offset:1024
	global_load_dword v126, v[0:1], off offset:2048
	global_load_dword v127, v[0:1], off offset:3072
	global_load_dword v128, v[4:5], off offset:1024
	global_load_dword v40, v[4:5], off offset:2048
	global_load_dword v41, v[4:5], off offset:3072
	global_load_dword v38, v[10:11], off
	global_load_dword v43, v[8:9], off offset:3072
	global_load_dword v129, v[8:9], off offset:-4096
	global_load_dword v42, v[8:9], off offset:2048
	global_load_dword v45, v[8:9], off offset:1024
	global_load_dword v44, v[8:9], off
	global_load_dword v47, v[6:7], off offset:3072
	global_load_dword v46, v[6:7], off offset:2048
	global_load_dword v49, v[6:7], off offset:1024
	global_load_dword v48, v[6:7], off
	v_and_b32_e32 v1, 7, v194
	v_and_b32_e32 v13, 7, v114
	s_addc_u32 s29, s95, 0
	s_add_i32 s0, 0, 0x4000
	v_lshl_or_b32 v12, v12, 3, v13
	v_lshlrev_b32_e32 v13, 5, v1
	v_lshlrev_b32_e32 v27, 8, v114
	v_mov_b32_e32 v7, s0
	v_add_u32_e32 v151, 0, v13
	v_or_b32_e32 v13, v27, v13
	s_movk_i32 s0, 0x240
	v_lshlrev_b32_e32 v0, 3, v1
	v_add_u32_e32 v152, 0, v13
	v_mad_u32_u24 v13, v1, s0, v12
	v_lshl_add_u32 v153, v13, 1, 0
	v_or_b32_e32 v13, 1, v0
	s_movk_i32 s0, 0x48
	v_or_b32_e32 v3, 64, v0
	v_lshlrev_b32_e32 v2, 2, v1
	v_lshlrev_b32_e32 v5, 4, v1
	v_mad_u32_u24 v13, v13, s0, v12
	v_mul_u32_u24_e32 v1, 0x480, v1
	v_lshlrev_b32_e32 v12, 1, v12
	v_readlane_b32 s3, v253, 45
	v_ashrrev_i32_e32 v51, 31, v50
	v_lshl_add_u32 v155, v13, 1, 0
	v_add3_u32 v162, s3, v1, v12
	v_mul_u32_u24_e32 v1, 0x90, v3
	v_add3_u32 v163, s3, v1, v12
	v_lshlrev_b64 v[12:13], 8, v[50:51]
	v_lshrrev_b32_e32 v28, 4, v112
	v_lshrrev_b32_e32 v51, 3, v142
	v_xor_b32_e32 v52, v51, v28
	v_bitop3_b32 v51, v28, v51, 4 bitop3:0x36
	v_lshlrev_b32_e32 v4, 7, v114
; template <int MODE>
; __device__ __forceinline__ void gla_item(const int TID, const Params& p, int l, int ci, int head, LAS unsigned char* lds, const float (&wg)[2][16], const float (&bg)[2], const float (&ngv)[16]) {
;     ...
;     { float* gb = (float*)(p.ws + WS_GB) + (size_t)(ci * 4 + head) * 8192;
; #pragma unroll
;       for (int i = 0; i < 4; ++i) { const int e = (i * 512 + tid) * 4; *(f32x4*)(gb + e) = *(const LAS f32x4*)(bfs + e); } }
;     } else {
;       __syncthreads();
; #pragma unroll
;       for (int i = 0; i < 4; ++i) { const int e = (i * 512 + tid) * 4; *(LAS f32x4*)(bfs + e) = gbv[i]; }
;       __syncthreads();
;     }
;     LAS bf16_t* vT = (LAS bf16_t*)(lds + GL_VT);
;     { const int r = tid >> 3, k8 = (tid & 7) * 8; const bool ok = r >= rmin;
;       if (!ok) { kw = (u32x4){0u, 0u, 0u, 0u}; qw = kw; }
;       float qv[8], kv[8];
; #pragma unroll
;       for (int i = 0; i < 4; ++i) { qv[2 * i] = bflo(qw[i]); qv[2 * i + 1] = bfhi(qw[i]); kv[2 * i] = bflo(kw[i]); kv[2 * i + 1] = bfhi(kw[i]); }
;       if (MODE == 0) { LAS bf16_t* kd0 = (LAS bf16_t*)(lds + GL_QE0); LAS bf16_t* kd1 = (LAS bf16_t*)(lds + GL_QE1);
; #pragma unroll
;           for (int i = 0; i < 8; ++i) { const int kk = k8 + i; kd0[kk * GLD + SWZ(kk, r)] = f2bf(kv[i] * __expf(bfs[63 * 64 + kk] - bfs[r * 64 + kk])); kd1[kk * GLD + SWZ(kk, r)] = f2bf(kv[i] * __expf(bbs[kk] - bbs[r * 64 + kk])); }
;       } else { LAS bf16_t* qe0 = (LAS bf16_t*)(lds + GL_QE0); LAS bf16_t* qe1 = (LAS bf16_t*)(lds + GL_QE1); LAS bf16_t* ke0 = (LAS bf16_t*)(lds + GL_KE0); LAS bf16_t* ke1 = (LAS bf16_t*)(lds + GL_KE1);
;           u32x4 a, b2, c2, d2;
; #pragma unroll
;           for (int i = 0; i < 4; ++i) { const int kk = k8 + 2 * i; const float f0 = bfs[r * 64 + kk], f1 = bfs[r * 64 + kk + 1], g0 = bbs[r * 64 + kk], g1 = bbs[r * 64 + kk + 1];
;               a[i] = cvt_pk_bf16(qv[2 * i] * 0.125f * __expf(f0), qv[2 * i + 1] * 0.125f * __expf(f1)); b2[i] = cvt_pk_bf16(qv[2 * i] * 0.125f * __expf(g0), qv[2 * i + 1] * 0.125f * __expf(g1));
;               c2[i] = cvt_pk_bf16(kv[2 * i] * __expf(-f0), kv[2 * i + 1] * __expf(-f1)); d2[i] = cvt_pk_bf16(kv[2 * i] * __expf(-g0), kv[2 * i + 1] * __expf(-g1)); }
;           *(LAS u32x4*)(qe0 + r * GLD + k8) = a; *(LAS u32x4*)(qe1 + r * GLD + k8) = b2; *(LAS u32x4*)(ke0 + r * GLD + k8) = c2; *(LAS u32x4*)(ke1 + r * GLD + k8) = d2; }
; #pragma unroll
	v_lshlrev_b32_e32 v98, 4, v51
	v_or_b32_e32 v51, 16, v142
	v_add3_u32 v130, 0, v4, v5
	v_lshlrev_b32_e32 v4, 2, v194
	s_add_i32 s1, 0, 0x8000
	v_lshrrev_b32_e32 v51, 3, v51
	v_add_u32_e32 v131, 0, v4
	v_add_u32_e32 v132, 8, v50
	v_mov_b32_e32 v6, s1
	v_cmp_gt_u32_e32 vcc, 64, v115
	s_movk_i32 s0, 0x80
	v_lshlrev_b32_e32 v97, 4, v52
	v_xor_b32_e32 v52, v51, v28
	v_bitop3_b32 v51, v51, v28, 4 bitop3:0x1e
	v_lshl_or_b32 v5, v132, 8, v182
	v_add_u32_e32 v135, 16, v50
	v_cndmask_b32_e32 v6, v6, v7, vcc
	v_add_u32_e32 v154, v151, v27
	v_cmp_gt_i32_e64 s[56:57], s0, v194
	v_add_u32_e32 v1, 0x7f00, v131
	v_add_u32_e32 v3, s1, v182
	v_cmp_gt_u32_e32 vcc, 64, v194
	s_movk_i32 s0, 0x900
	v_mul_u32_u24_e32 v27, 0x48, v142
	v_lshlrev_b32_e32 v100, 4, v51
	v_or_b32_e32 v51, 32, v142
	v_add_u32_e32 v133, 0, v5
	v_lshl_or_b32 v5, v135, 8, v182
	v_add_u32_e32 v137, 24, v50
	v_cndmask_b32_e32 v164, v3, v1, vcc
	v_mul_lo_u32 v1, v50, s0
	v_lshlrev_b32_e32 v27, 1, v27
	v_lshrrev_b32_e32 v51, 3, v51
	v_add_u32_e32 v136, 0, v5
	v_lshl_or_b32 v5, v137, 8, v182
	v_add_u32_e32 v139, 32, v50
	v_add3_u32 v1, s3, v1, v27
	v_lshlrev_b32_e32 v99, 4, v52
	v_xor_b32_e32 v52, v51, v28
	v_bitop3_b32 v51, v51, v28, 4 bitop3:0x1e
	s_ashr_i32 s3, s2, 31
	v_add_u32_e32 v138, 0, v5
	v_lshl_or_b32 v5, v139, 8, v182
	v_add_u32_e32 v141, 40, v50
	v_lshlrev_b32_e32 v102, 4, v51
	v_or_b32_e32 v51, 48, v142
	s_lshl_b64 s[0:1], s[2:3], 9
	v_add_u32_e32 v140, 0, v5
	v_lshl_or_b32 v5, v141, 8, v182
	v_add_u32_e32 v145, 48, v50
	v_lshrrev_b32_e32 v51, 3, v51
	s_add_u32 s0, s0, 0x47820000
	v_add_u32_e32 v144, 0, v5
	v_lshl_or_b32 v5, v145, 8, v182
	v_add_u32_e32 v147, 56, v50
	v_lshlrev_b32_e32 v101, 4, v52
	v_xor_b32_e32 v52, v51, v28
	s_addc_u32 s1, s1, 0
	v_add_u32_e32 v146, 0, v5
	v_lshl_or_b32 v5, v147, 8, v182
	v_lshlrev_b32_e32 v103, 4, v52
	v_lshl_add_u64 v[52:53], s[0:1], 0, v[12:13]
	s_lshl_b64 s[0:1], s[2:3], 15
	v_add_u32_e32 v148, 0, v5
	v_ashrrev_i32_e32 v5, 7, v194
	s_add_u32 s58, s0, 0x4cfc4600
	v_lshlrev_b32_e32 v7, 12, v5
	v_cmp_gt_i32_e64 s[40:41], 0, v5
	v_cmp_lt_i32_e64 s[42:43], 0, v5
	v_cmp_gt_i32_e64 s[44:45], 1, v5
	v_cmp_lt_i32_e64 s[46:47], 1, v5
	v_cmp_gt_i32_e64 s[48:49], 2, v5
	v_cmp_lt_i32_e64 s[50:51], 2, v5
	v_cmp_gt_i32_e64 s[52:53], 3, v5
	v_cmp_lt_i32_e64 s[54:55], 3, v5
	v_lshlrev_b32_e32 v26, 4, v194
	v_ashrrev_i32_e32 v5, 31, v4
	s_addc_u32 s59, s1, 0
	v_add3_u32 v149, v6, v7, v182
	v_add_u32_e32 v6, 0x800, v4
	v_add_u32_e32 v8, 0x1000, v4
	v_add_u32_e32 v10, 0x1800, v4
	v_lshl_add_u64 v[54:55], v[4:5], 2, s[58:59]
	v_and_b32_e32 v4, 0x300, v26
	v_lshl_or_b32 v4, v50, 10, v4
	v_ashrrev_i32_e32 v5, 31, v4
	v_or_b32_e32 v4, v4, v142
	v_ashrrev_i32_e32 v7, 31, v6
	v_lshl_add_u64 v[56:57], v[4:5], 1, s[0:1]
	v_ashrrev_i32_e32 v5, 31, v4
	v_lshl_add_u64 v[58:59], v[6:7], 2, s[58:59]
	v_lshl_add_u64 v[64:65], v[4:5], 1, s[0:1]
	s_add_u32 s0, s0, 0x415a4000
	v_or_b32_e32 v6, 0xf0, v4
	s_addc_u32 s1, s1, 0
	v_ashrrev_i32_e32 v7, 31, v6
	v_lshl_add_u64 v[66:67], v[6:7], 1, s[0:1]
	v_or_b32_e32 v6, 0xb0, v4
	v_ashrrev_i32_e32 v7, 31, v6
	v_lshl_add_u64 v[68:69], v[6:7], 1, s[0:1]
	v_or_b32_e32 v6, 0x70, v4
	v_ashrrev_i32_e32 v7, 31, v6
	v_lshl_add_u64 v[70:71], v[6:7], 1, s[0:1]
	v_or_b32_e32 v6, 48, v4
	v_ashrrev_i32_e32 v7, 31, v6
	v_lshl_add_u64 v[72:73], v[6:7], 1, s[0:1]
	v_or_b32_e32 v6, 0xe0, v4
	v_ashrrev_i32_e32 v7, 31, v6
	v_lshl_add_u64 v[74:75], v[6:7], 1, s[0:1]
	v_or_b32_e32 v6, 0xa0, v4
	v_ashrrev_i32_e32 v7, 31, v6
	v_lshl_add_u64 v[76:77], v[6:7], 1, s[0:1]
	v_or_b32_e32 v6, 0x60, v4
	v_ashrrev_i32_e32 v7, 31, v6
	v_lshl_add_u64 v[78:79], v[6:7], 1, s[0:1]
	v_or_b32_e32 v6, 32, v4
	v_ashrrev_i32_e32 v7, 31, v6
	v_lshl_add_u64 v[80:81], v[6:7], 1, s[0:1]
	v_or_b32_e32 v6, 0xd0, v4
	v_ashrrev_i32_e32 v7, 31, v6
	v_lshl_add_u64 v[82:83], v[6:7], 1, s[0:1]
	v_or_b32_e32 v6, 0x90, v4
	v_ashrrev_i32_e32 v7, 31, v6
	v_lshl_add_u64 v[84:85], v[6:7], 1, s[0:1]
	v_or_b32_e32 v6, 0x50, v4
	v_ashrrev_i32_e32 v7, 31, v6
	v_lshl_add_u64 v[86:87], v[6:7], 1, s[0:1]
	v_or_b32_e32 v6, 16, v4
	v_lshl_or_b32 v3, v50, 4, v142
	v_ashrrev_i32_e32 v7, 31, v6
	v_bfe_u32 v3, v3, 3, 3
	v_cmp_lt_i32_e32 vcc, -1, v50
	v_lshl_add_u64 v[88:89], v[6:7], 1, s[0:1]
	v_or_b32_e32 v6, 0xc0, v4
	v_cndmask_b32_e32 v3, 0, v3, vcc
	v_ashrrev_i32_e32 v7, 31, v6
	v_xor_b32_e32 v29, v3, v28
	v_bitop3_b32 v3, v3, v28, 4 bitop3:0x1e
	v_bitop3_b32 v28, v51, v28, 4 bitop3:0x1e
	v_lshl_add_u64 v[90:91], v[6:7], 1, s[0:1]
	v_or_b32_e32 v6, 0x80, v4
	v_or_b32_e32 v4, 64, v4
	v_lshlrev_b32_e32 v18, 7, v50
	v_lshlrev_b32_e32 v19, 7, v132
	v_lshlrev_b32_e32 v20, 7, v135
	v_lshlrev_b32_e32 v21, 7, v137
	v_lshlrev_b32_e32 v22, 7, v139
	v_lshlrev_b32_e32 v23, 7, v141
	v_lshlrev_b32_e32 v24, 7, v145
	v_lshlrev_b32_e32 v25, 7, v147
	v_ashrrev_i32_e32 v9, 31, v8
	v_ashrrev_i32_e32 v11, 31, v10
	v_add_u32_e32 v27, 0, v27
	v_lshlrev_b32_e32 v29, 4, v29
	v_lshlrev_b32_e32 v3, 4, v3
	v_lshlrev_b32_e32 v28, 4, v28
	v_ashrrev_i32_e32 v7, 31, v6
	v_ashrrev_i32_e32 v5, 31, v4
	v_cmp_lt_u32_e64 s[38:39], 63, v115
	v_add_u32_e32 v150, 0, v26
	v_add_u32_e32 v156, 0x90, v155
	v_add_u32_e32 v157, 0x120, v155
	v_add_u32_e32 v158, 0x1b0, v155
	v_add_u32_e32 v159, 0x240, v155
	v_add_u32_e32 v160, 0x2d0, v155
	v_add_u32_e32 v161, 0x360, v155
	v_or_b32_e32 v52, v52, v182
	v_lshl_add_u64 v[60:61], v[8:9], 2, s[58:59]
	v_lshl_add_u64 v[62:63], v[10:11], 2, s[58:59]
	v_lshl_add_u64 v[92:93], v[6:7], 1, s[0:1]
	v_lshl_add_u64 v[94:95], v[4:5], 1, s[0:1]
	v_lshlrev_b32_e32 v182, 1, v0
	v_lshlrev_b32_e32 v96, 1, v2
	v_add_u32_e32 v51, 0, v18
	v_add_u32_e32 v165, 0, v19
	v_add_u32_e32 v166, 0, v20
	v_add_u32_e32 v167, 0, v21
	v_add_u32_e32 v168, 0, v22
	v_add_u32_e32 v169, 0, v23
	v_add_u32_e32 v170, 0, v24
	v_add_u32_e32 v171, 0, v25
	v_add_u32_e32 v172, v1, v29
	v_add_u32_e32 v173, v27, v97
	v_add_u32_e32 v174, v1, v3
	v_add_u32_e32 v175, v27, v98
	v_add_u32_e32 v176, v27, v99
	v_add_u32_e32 v177, v27, v100
	v_add_u32_e32 v178, v27, v101
	v_add_u32_e32 v179, v27, v102
	v_add_u32_e32 v180, v27, v103
	v_add_u32_e32 v181, v27, v28
	s_mov_b32 s62, 0
	s_branch .LBB0_740

; #define LAS __attribute__((address_space(3)))
; __device__ __forceinline__ float bflo(unsigned w) { return __uint_as_float(w << 16); }
; __device__ __forceinline__ float bfhi(unsigned w) { return __uint_as_float(w & 0xffff0000u); }
; template <int MODE>
; __device__ __forceinline__ void gla_item(const int TID, const Params& p, int l, int ci, int head, LAS unsigned char* lds, const float (&wg)[2][16], const float (&bg)[2], const float (&ngv)[16]) {
;     ...
;     { const int r = tid >> 3, k8 = (tid & 7) * 8; const int rc = r >= rmin ? r : rmin; const bf16_t* rowp = cols + (size_t)(tok0 + rc) * NINP;
;       kw = *(const u32x4*)(rowp + C_K + head * 64 + k8); if (MODE == 1) qw = *(const u32x4*)(rowp + C_Q + head * 64 + k8);
; #pragma unroll
;       for (int hh = 0; hh < 2; ++hh) { vwp[hh] = *(const u32x4*)(rowp + C_V + head * 128 + ((tid & 7) + 8 * hh) * 8); if (MODE == 1) gwp[hh] = *(const u32x4*)(rowp + C_GB + head * 128 + (tid & 7) * 16 + hh * 8); } }
;     if (MODE == 0) {
;     { const int r = tid >> 3, j4 = (tid & 7) * 4; f32x4 v = (f32x4){0.f, 0.f, 0.f, 0.f};
;       { const int rc = r >= rmin ? r : rmin; const u32x2 w = *(const u32x2*)(cols + (size_t)(tok0 + rc) * NINP + C_GLR + j4); if (r >= rmin) { v[0] = bflo(w.x); v[1] = bfhi(w.x); v[2] = bflo(w.y); v[3] = bfhi(w.y); } }
;       *(LAS f32x4*)(glr_s + r * 32 + j4) = v; }
.LBB0_745:
	s_lshl_b32 s0, s3, 6
	s_and_b32 s8, s2, 3
	s_add_i32 s0, s0, s23
	s_cmp_eq_u32 s3, 0
	s_cselect_b32 s3, 48, 0
	v_max_i32_e32 v0, s3, v114
	s_sub_i32 s0, s0, 48
	v_add_u32_e32 v2, s0, v0
	v_mov_b64_e32 v[0:1], s[28:29]
	v_mad_i64_i32 v[4:5], s[0:1], v2, s4, v[0:1]
	s_lshl_b32 s24, s8, 7
	v_lshl_add_u64 v[0:1], v[4:5], 0, s[24:25]
	s_lshl_b32 s24, s8, 8
	v_lshl_add_u64 v[0:1], v[0:1], 0, v[182:183]
	v_lshl_add_u64 v[2:3], v[4:5], 0, s[24:25]
	v_lshl_add_u64 v[2:3], v[2:3], 0, v[182:183]
	s_cmp_lg_u32 s62, 0
	s_cbranch_scc1 .Lgp0_havek
	flat_load_dwordx4 v[26:29], v[0:1] offset:2560
	flat_load_dwordx4 v[22:25], v[2:3] offset:3072
	flat_load_dwordx4 v[18:21], v[2:3] offset:3200
	s_branch .Lgp0_kdone
.Lgp0_havek:
	v_mov_b32_e32 v26, v196
	v_mov_b32_e32 v27, v197
	v_mov_b32_e32 v28, v198
	v_mov_b32_e32 v29, v199
	v_mov_b32_e32 v22, v200
	v_mov_b32_e32 v23, v201
	v_mov_b32_e32 v24, v202
	v_mov_b32_e32 v25, v203
	v_mov_b32_e32 v18, v204
	v_mov_b32_e32 v19, v205
	v_mov_b32_e32 v20, v206
	v_mov_b32_e32 v21, v207
.Lgp0_kdone:
	v_cmp_gt_i32_e64 s[58:59], s3, v114
	v_cmp_le_i32_e32 vcc, s3, v114
	v_mov_b32_e32 v0, 0
	v_mov_b32_e32 v1, 0
	v_mov_b32_e32 v2, 0
	v_mov_b32_e32 v3, 0
	s_and_saveexec_b64 s[0:1], vcc
	s_cbranch_execz .LBB0_747
	v_mov_b32_e32 v97, v183
	v_lshl_add_u64 v[0:1], v[4:5], 0, v[96:97]
	v_add_co_u32_e32 v0, vcc, 0x5000, v0
	s_nop 1
	v_addc_co_u32_e32 v1, vcc, 0, v1, vcc
	s_cmp_lg_u32 s62, 0
	s_cbranch_scc1 .Lgp0_haveg
	flat_load_dwordx2 v[2:3], v[0:1] offset:1024
	s_branch .Lgp0_gdone
.Lgp0_haveg:
	v_mov_b32_e32 v2, v208
	v_mov_b32_e32 v3, v209
	s_branch .Lgp0_gnowait

; #define LAS __attribute__((address_space(3)))
; __device__ __forceinline__ float bflo(unsigned w) { return __uint_as_float(w << 16); }
; __device__ __forceinline__ float bfhi(unsigned w) { return __uint_as_float(w & 0xffff0000u); }
; __device__ __forceinline__ float logsig(float x) { return -(fmaxf(-x, 0.f) + __logf(1.0f + __expf(-fabsf(x)))); }
; template <int MODE>
; __device__ __forceinline__ void gla_item(const int TID, const Params& p, int l, int ci, int head, LAS unsigned char* lds, const float (&wg)[2][16], const float (&bg)[2], const float (&ngv)[16]) {
;     ...
;       { const int rc = r >= rmin ? r : rmin; const u32x2 w = *(const u32x2*)(cols + (size_t)(tok0 + rc) * NINP + C_GLR + j4); if (r >= rmin) { v[0] = bflo(w.x); v[1] = bfhi(w.x); v[2] = bflo(w.y); v[3] = bfhi(w.y); } }
;       *(LAS f32x4*)(glr_s + r * 32 + j4) = v; }
;     __syncthreads();
;     { const int kk = tid & 63, rb = tid >> 6;
; #pragma unroll
;       for (int i = 0; i < 8; ++i) { const int r = rb + 8 * i; float x0 = bg[0], x1 = bg[1]; f32x4 gr[8];
; #pragma unroll
;           for (int j4 = 0; j4 < 8; ++j4) gr[j4] = *(const LAS f32x4*)(glr_s + r * 32 + j4 * 4);
; #pragma unroll
;           for (int j = 0; j < 16; ++j) { x0 += gr[j >> 2][j & 3] * wg[0][j]; x1 += gr[4 + (j >> 2)][j & 3] * wg[1][j]; }
;           const bool ok = r >= rmin; bfs[r * 64 + kk] = ok ? logsig(x0) * 0.0625f : 0.f; bbs[r * 64 + kk] = ok ? logsig(x1) * 0.0625f : 0.f; } }
.Lgp0_gnowait:
	v_lshlrev_b32_e32 v0, 16, v2
	v_and_b32_e32 v1, 0xffff0000, v2
	v_lshlrev_b32_e32 v2, 16, v3
	v_and_b32_e32 v3, 0xffff0000, v3
.LBB0_747:
	s_or_b64 exec, exec, s[0:1]
	s_cmp_lg_u32 s62, 0
	s_cbranch_scc1 .Lgp0_nodrain
	s_waitcnt vmcnt(0)
.Lgp0_nodrain:
	s_mov_b32 s62, 0
	s_add_i32 s64, s2, s96
	s_cmpk_gt_i32 s64, 0x627
	s_cbranch_scc1 .Lgp0_nopf
	s_ashr_i32 s65, s64, 2
	s_cmpk_lt_i32 s65, 0x82
	s_cbranch_scc1 .Lgp0_a
	s_sub_i32 s66, s65, 0x82
	s_mul_i32 s67, s66, 0x7c2
	s_lshr_b32 s67, s67, 16
	s_mul_i32 s68, s67, 33
	s_sub_i32 s66, s66, s68
	s_mul_i32 s68, s67, 0x810
	s_add_i32 s68, s68, 0x2020
	s_branch .Lgp0_c
.Lgp0_a:
	s_cmpk_ge_i32 s65, 65
	s_cselect_b32 s67, 65, 0
	s_cselect_b32 s68, 0x1010, 0
	s_sub_i32 s66, s65, s67
.Lgp0_c:
	s_lshl_b32 s67, s66, 6
	s_add_i32 s68, s68, s67
	s_sub_i32 s68, s68, 48
	s_cmp_eq_u32 s66, 0
	s_cselect_b32 s69, 48, 0
	v_max_i32_e32 v210, s69, v114
	v_add_u32_e32 v210, s68, v210
	v_mul_lo_u32 v210, v210, s4
	s_and_b32 s70, s2, 3
	s_lshl_b32 s71, s70, 7
	s_lshl_b32 s72, s70, 8
	v_add3_u32 v211, v210, s71, v182
	v_add3_u32 v212, v210, s72, v182
	v_add_u32_e32 v213, v210, v96
	v_add_u32_e32 v213, 0x5400, v213
	global_load_dwordx4 v[196:199], v211, s[28:29] offset:2560
	global_load_dwordx4 v[200:203], v212, s[28:29] offset:3072
	global_load_dwordx4 v[204:207], v212, s[28:29] offset:3200
	global_load_dwordx2 v[208:209], v213, s[28:29]
	s_mov_b32 s62, 1
.Lgp0_nopf:
	v_cmp_le_i32_e32 vcc, s3, v50
	ds_write_b128 v130, v[0:3]
	s_waitcnt lgkmcnt(0)
	s_barrier
	s_and_saveexec_b64 s[0:1], vcc
	s_xor_b64 s[60:61], exec, s[0:1]
	s_cbranch_execz .LBB0_749
	ds_read_b128 v[0:3], v51 offset:64
	s_mov_b32 s8, 0xbfb8aa3b
	s_waitcnt lgkmcnt(0)
	v_fma_f32 v4, v0, v124, v122
	v_fmac_f32_e32 v4, v1, v125
	v_fmac_f32_e32 v4, v2, v126
	v_fmac_f32_e32 v4, v3, v127
	ds_read_b128 v[0:3], v51 offset:80
	s_waitcnt lgkmcnt(0)
	v_fmac_f32_e32 v4, v0, v129
	v_fmac_f32_e32 v4, v1, v128
	v_fmac_f32_e32 v4, v2, v40
	v_fmac_f32_e32 v4, v3, v41
	ds_read_b128 v[0:3], v51 offset:96
	s_waitcnt lgkmcnt(0)
	v_pk_mul_f32 v[0:1], v[0:1], v[44:45]
	s_nop 0
	v_add_f32_e32 v0, v4, v0
	v_add_f32_e32 v4, v0, v1
	v_pk_mul_f32 v[0:1], v[2:3], v[42:43]
	s_nop 0
	v_add_f32_e32 v0, v4, v0
	v_add_f32_e32 v4, v0, v1
	ds_read_b128 v[0:3], v51 offset:112
	s_waitcnt lgkmcnt(0)
	v_pk_mul_f32 v[0:1], v[0:1], v[38:39]
	s_nop 0
	v_add_f32_e32 v0, v4, v0
	v_add_f32_e32 v4, v0, v1
	v_pk_mul_f32 v[0:1], v[2:3], v[32:33]
	s_nop 0
	v_add_f32_e32 v0, v4, v0
	v_add_f32_e32 v12, v0, v1
	ds_read_b128 v[0:3], v51
	ds_read_b128 v[4:7], v51 offset:16
	ds_read_b128 v[8:11], v51 offset:32
	ds_read_b128 v[98:101], v51 offset:48
	s_waitcnt lgkmcnt(3)
	v_fma_f32 v13, v0, v117, v116
	v_fmac_f32_e32 v13, v1, v118
	v_fmac_f32_e32 v13, v2, v119
	v_fmac_f32_e32 v13, v3, v120
	s_waitcnt lgkmcnt(2)
	v_fmac_f32_e32 v13, v4, v123
	v_fmac_f32_e32 v13, v5, v121
	v_fmac_f32_e32 v13, v6, v30
	v_fmac_f32_e32 v13, v7, v31
	s_waitcnt lgkmcnt(1)
	v_pk_mul_f32 v[0:1], v[8:9], v[48:49]
	s_nop 0
	v_add_f32_e32 v0, v13, v0
	v_add_f32_e32 v2, v0, v1
	v_pk_mul_f32 v[0:1], v[10:11], v[46:47]
	s_nop 0
	v_add_f32_e32 v0, v2, v0
	v_add_f32_e32 v2, v0, v1
	s_waitcnt lgkmcnt(0)
	v_pk_mul_f32 v[0:1], v[98:99], v[36:37]
	s_nop 0
	v_add_f32_e32 v0, v2, v0
	v_add_f32_e32 v2, v0, v1
	v_pk_mul_f32 v[0:1], v[100:101], v[34:35]
	s_nop 0
	v_add_f32_e32 v0, v2, v0
	v_add_f32_e32 v0, v0, v1
	v_max_f32_e64 v1, -v0, 0
	v_mul_f32_e64 v0, |v0|, s8
	v_exp_f32_e32 v0, v0
	s_nop 0
	v_add_f32_e32 v0, 1.0, v0
	v_cmp_gt_f32_e32 vcc, s19, v0
	s_nop 1
	v_cndmask_b32_e64 v2, 0, 32, vcc
	v_ldexp_f32 v0, v0, v2
	v_log_f32_e32 v0, v0
	s_nop 0
	v_mul_f32_e32 v2, 0x3f317217, v0
	v_fma_f32 v2, v0, s15, -v2
	v_fmac_f32_e32 v2, 0x3377d1cf, v0
	v_fmac_f32_e32 v2, 0x3f317217, v0
	v_cmp_lt_f32_e64 s[0:1], |v0|, s7
	s_nop 1
	v_cndmask_b32_e64 v0, v0, v2, s[0:1]
	v_cndmask_b32_e32 v2, 0, v230, vcc
	v_sub_f32_e32 v0, v0, v2
	v_add_f32_e32 v0, v1, v0
	v_mul_f32_e64 v1, |v12|, s8
	v_exp_f32_e32 v1, v1
	v_mul_f32_e32 v0, 0xbd800000, v0
	ds_write_b32 v131, v0 offset:16384
	v_max_f32_e64 v0, -v12, 0
	v_add_f32_e32 v1, 1.0, v1
	v_cmp_gt_f32_e32 vcc, s19, v1
	s_nop 1
	v_cndmask_b32_e64 v2, 0, 32, vcc
	v_ldexp_f32 v1, v1, v2
	v_log_f32_e32 v1, v1
	s_nop 0
	v_mul_f32_e32 v2, 0x3f317217, v1
	v_fma_f32 v2, v1, s15, -v2
	v_fmac_f32_e32 v2, 0x3377d1cf, v1
	v_fmac_f32_e32 v2, 0x3f317217, v1
	v_cmp_lt_f32_e64 s[0:1], |v1|, s7
	s_nop 1
	v_cndmask_b32_e64 v1, v1, v2, s[0:1]
	v_cndmask_b32_e32 v2, 0, v230, vcc
	v_sub_f32_e32 v1, v1, v2
	v_add_f32_e32 v0, v0, v1
	v_mul_f32_e32 v0, 0xbd800000, v0
; #define LAS __attribute__((address_space(3)))
; __device__ __forceinline__ float logsig(float x) { return -(fmaxf(-x, 0.f) + __logf(1.0f + __expf(-fabsf(x)))); }
; template <int MODE>
; __device__ __forceinline__ void gla_item(const int TID, const Params& p, int l, int ci, int head, LAS unsigned char* lds, const float (&wg)[2][16], const float (&bg)[2], const float (&ngv)[16]) {
;     ...
;     { const int kk = tid & 63, rb = tid >> 6;
; #pragma unroll
;       for (int i = 0; i < 8; ++i) { const int r = rb + 8 * i; float x0 = bg[0], x1 = bg[1]; f32x4 gr[8];
; #pragma unroll
;           for (int j4 = 0; j4 < 8; ++j4) gr[j4] = *(const LAS f32x4*)(glr_s + r * 32 + j4 * 4);
; #pragma unroll
;           for (int j = 0; j < 16; ++j) { x0 += gr[j >> 2][j & 3] * wg[0][j]; x1 += gr[4 + (j >> 2)][j & 3] * wg[1][j]; }
;           const bool ok = r >= rmin; bfs[r * 64 + kk] = ok ? logsig(x0) * 0.0625f : 0.f; bbs[r * 64 + kk] = ok ? logsig(x1) * 0.0625f : 0.f; } }
.LBB0_749:
	s_andn2_saveexec_b64 s[0:1], s[60:61]
	v_mov_b32_e32 v0, 0
	ds_write_b32 v131, v183 offset:16384
	s_or_b64 exec, exec, s[0:1]
	ds_write_b32 v131, v0 offset:32768
	v_cmp_le_i32_e32 vcc, s3, v132
	v_mov_b32_e32 v0, 0
	v_mov_b32_e32 v2, 0
	v_mov_b32_e32 v3, 0
	s_and_saveexec_b64 s[60:61], vcc
	s_cbranch_execz .LBB0_753
	ds_read_b128 v[2:5], v165 offset:64
	s_mov_b32 s8, 0xbfb8aa3b
	s_waitcnt lgkmcnt(0)
	v_fma_f32 v1, v2, v124, v122
	v_fmac_f32_e32 v1, v3, v125
	v_fmac_f32_e32 v1, v4, v126
	v_fmac_f32_e32 v1, v5, v127
	ds_read_b128 v[2:5], v165 offset:80
	s_waitcnt lgkmcnt(0)
	v_fmac_f32_e32 v1, v2, v129
	v_fmac_f32_e32 v1, v3, v128
	v_pk_mul_f32 v[2:3], v[4:5], v[40:41]
	s_nop 0
	v_add_f32_e32 v1, v1, v2
	v_add_f32_e32 v1, v1, v3
	ds_read_b128 v[2:5], v165 offset:96
	s_waitcnt lgkmcnt(0)
	v_pk_mul_f32 v[2:3], v[2:3], v[44:45]
	s_nop 0
	v_add_f32_e32 v1, v1, v2
	v_add_f32_e32 v1, v1, v3
	v_pk_mul_f32 v[2:3], v[4:5], v[42:43]
	s_nop 0
	v_add_f32_e32 v1, v1, v2
	v_add_f32_e32 v1, v1, v3
	ds_read_b128 v[2:5], v165 offset:112
	s_waitcnt lgkmcnt(0)
	v_pk_mul_f32 v[2:3], v[2:3], v[38:39]
	s_nop 0
	v_add_f32_e32 v1, v1, v2
	v_add_f32_e32 v1, v1, v3
	v_pk_mul_f32 v[2:3], v[4:5], v[32:33]
	s_nop 0
	v_add_f32_e32 v1, v1, v2
	v_add_f32_e32 v1, v1, v3
	ds_read_b128 v[2:5], v165
	ds_read_b128 v[6:9], v165 offset:16
	ds_read_b128 v[10:13], v165 offset:32
	ds_read_b128 v[98:101], v165 offset:48
	s_waitcnt lgkmcnt(3)
	v_fma_f32 v97, v2, v117, v116
	v_fmac_f32_e32 v97, v3, v118
	v_fmac_f32_e32 v97, v4, v119
	v_fmac_f32_e32 v97, v5, v120
	s_waitcnt lgkmcnt(2)
	v_fmac_f32_e32 v97, v6, v123
	v_fmac_f32_e32 v97, v7, v121
	v_pk_mul_f32 v[2:3], v[8:9], v[30:31]
	s_nop 0
	v_add_f32_e32 v2, v97, v2
	v_add_f32_e32 v4, v2, v3
	s_waitcnt lgkmcnt(1)
	v_pk_mul_f32 v[2:3], v[10:11], v[48:49]
	s_nop 0
	v_add_f32_e32 v2, v4, v2
	v_add_f32_e32 v4, v2, v3
	v_pk_mul_f32 v[2:3], v[12:13], v[46:47]
	s_nop 0
	v_add_f32_e32 v2, v4, v2
	v_add_f32_e32 v4, v2, v3
	s_waitcnt lgkmcnt(0)
	v_pk_mul_f32 v[2:3], v[98:99], v[36:37]
	s_nop 0
	v_add_f32_e32 v2, v4, v2
	v_add_f32_e32 v4, v2, v3
	v_pk_mul_f32 v[2:3], v[100:101], v[34:35]
	s_nop 0
	v_add_f32_e32 v2, v4, v2
	v_add_f32_e32 v3, v2, v3
	v_max_f32_e64 v2, -v3, 0
	v_mul_f32_e64 v3, |v3|, s8
	v_exp_f32_e32 v3, v3
	s_nop 0
	v_add_f32_e32 v3, 1.0, v3
	v_cmp_gt_f32_e32 vcc, s19, v3
	s_nop 1
	v_cndmask_b32_e64 v4, 0, 32, vcc
	v_ldexp_f32 v3, v3, v4
	v_log_f32_e32 v3, v3
	s_nop 0
	v_mul_f32_e32 v4, 0x3f317217, v3
	v_fma_f32 v4, v3, s15, -v4
	v_fmac_f32_e32 v4, 0x3377d1cf, v3
	v_fmac_f32_e32 v4, 0x3f317217, v3
	v_cmp_lt_f32_e64 s[0:1], |v3|, s7
	s_nop 1
	v_cndmask_b32_e64 v3, v3, v4, s[0:1]
	v_cndmask_b32_e32 v4, 0, v230, vcc
	v_sub_f32_e32 v4, v3, v4
	v_max_f32_e64 v3, -v1, 0
	v_mul_f32_e64 v1, |v1|, s8
	v_exp_f32_e32 v1, v1
	s_nop 0
	v_add_f32_e32 v1, 1.0, v1
	v_cmp_gt_f32_e32 vcc, s19, v1
	s_nop 1
	v_cndmask_b32_e64 v5, 0, 32, vcc
	v_ldexp_f32 v1, v1, v5
	v_log_f32_e32 v1, v1
	s_nop 0
	v_mul_f32_e32 v5, 0x3f317217, v1
	v_fma_f32 v5, v1, s15, -v5
	v_fmac_f32_e32 v5, 0x3377d1cf, v1
	v_fmac_f32_e32 v5, 0x3f317217, v1
	v_cmp_lt_f32_e64 s[0:1], |v1|, s7
	s_nop 1
	v_cndmask_b32_e64 v1, v1, v5, s[0:1]
	v_cndmask_b32_e32 v5, 0, v230, vcc
	v_sub_f32_e32 v5, v1, v5
	v_pk_add_f32 v[2:3], v[2:3], v[4:5]
	s_mov_b32 s0, 0xbd800000
	v_pk_mul_f32 v[2:3], v[2:3], s[0:1] op_sel_hi:[1,0]
.LBB0_753:
	s_or_b64 exec, exec, s[60:61]
	v_cmp_le_i32_e32 vcc, s3, v135
	v_mov_b32_e32 v1, 0
	ds_write2st64_b32 v133, v2, v3 offset0:64 offset1:128
	s_and_saveexec_b64 s[60:61], vcc
	s_cbranch_execz .LBB0_755
	ds_read_b128 v[0:3], v166 offset:112
	s_mov_b32 s8, 0xbfb8aa3b
	s_waitcnt lgkmcnt(0)
	v_pk_mul_f32 v[6:7], v[32:33], v[2:3]
	v_pk_mul_f32 v[8:9], v[38:39], v[0:1]
	ds_read_b128 v[0:3], v166 offset:96
	s_waitcnt lgkmcnt(0)
	v_pk_mul_f32 v[10:11], v[42:43], v[2:3]
	v_pk_mul_f32 v[12:13], v[44:45], v[0:1]
	ds_read_b128 v[0:3], v166 offset:80
	s_waitcnt lgkmcnt(0)
	v_pk_mul_f32 v[98:99], v[40:41], v[2:3]
	ds_read_b128 v[2:5], v166 offset:64
	s_waitcnt lgkmcnt(0)
	v_fma_f32 v2, v124, v2, v122
	v_fmac_f32_e32 v2, v125, v3
	v_fmac_f32_e32 v2, v126, v4
	v_fmac_f32_e32 v2, v127, v5
	v_fmac_f32_e32 v2, v129, v0
	v_fmac_f32_e32 v2, v128, v1
	v_add_f32_e32 v0, v98, v2
	v_add_f32_e32 v0, v99, v0
	v_add_f32_e32 v0, v12, v0
	v_add_f32_e32 v0, v13, v0
	v_add_f32_e32 v0, v10, v0
	v_add_f32_e32 v0, v11, v0
	v_add_f32_e32 v0, v8, v0
	v_add_f32_e32 v0, v9, v0
	v_add_f32_e32 v0, v6, v0
	v_add_f32_e32 v12, v7, v0
	ds_read_b128 v[0:3], v166
	ds_read_b128 v[4:7], v166 offset:16
	ds_read_b128 v[8:11], v166 offset:32
	ds_read_b128 v[98:101], v166 offset:48
	s_waitcnt lgkmcnt(3)
	v_fma_f32 v13, v0, v117, v116
	v_fmac_f32_e32 v13, v1, v118
	v_fmac_f32_e32 v13, v2, v119
	v_fmac_f32_e32 v13, v3, v120
	s_waitcnt lgkmcnt(2)
	v_fmac_f32_e32 v13, v4, v123
	v_fmac_f32_e32 v13, v5, v121
	v_pk_mul_f32 v[0:1], v[6:7], v[30:31]
	v_mul_f32_e64 v3, |v12|, s8
	v_add_f32_e32 v0, v13, v0
	v_add_f32_e32 v2, v0, v1
	s_waitcnt lgkmcnt(1)
	v_pk_mul_f32 v[0:1], v[8:9], v[48:49]
	v_exp_f32_e32 v3, v3
	v_add_f32_e32 v0, v2, v0
	v_add_f32_e32 v2, v0, v1
	v_pk_mul_f32 v[0:1], v[10:11], v[46:47]
	v_add_f32_e32 v3, 1.0, v3
	v_add_f32_e32 v0, v2, v0
	v_add_f32_e32 v2, v0, v1
	s_waitcnt lgkmcnt(0)
	v_pk_mul_f32 v[0:1], v[98:99], v[36:37]
	s_nop 0
	v_add_f32_e32 v0, v2, v0
	v_add_f32_e32 v2, v0, v1
	v_pk_mul_f32 v[0:1], v[100:101], v[34:35]
	s_nop 0
	v_add_f32_e32 v0, v2, v0
	v_add_f32_e32 v1, v0, v1
	v_max_f32_e64 v0, -v1, 0
	v_mul_f32_e64 v1, |v1|, s8
	v_exp_f32_e32 v1, v1
	s_nop 0
	v_add_f32_e32 v1, 1.0, v1
	v_cmp_gt_f32_e32 vcc, s19, v1
	s_nop 1
	v_cndmask_b32_e64 v2, 0, 32, vcc
	v_ldexp_f32 v1, v1, v2
	v_log_f32_e32 v1, v1
	s_nop 0
	v_mul_f32_e32 v2, 0x3f317217, v1
	v_fma_f32 v2, v1, s15, -v2
	v_fmac_f32_e32 v2, 0x3377d1cf, v1
	v_fmac_f32_e32 v2, 0x3f317217, v1
	v_cmp_lt_f32_e64 s[0:1], |v1|, s7
	s_nop 1
	v_cndmask_b32_e64 v1, v1, v2, s[0:1]
	v_cndmask_b32_e32 v2, 0, v230, vcc
	v_cmp_gt_f32_e32 vcc, s19, v3
	v_sub_f32_e32 v2, v1, v2
	v_max_f32_e64 v1, -v12, 0
	v_cndmask_b32_e64 v4, 0, 32, vcc
	v_ldexp_f32 v3, v3, v4
	v_log_f32_e32 v3, v3
	s_nop 0
	v_mul_f32_e32 v4, 0x3f317217, v3
	v_fma_f32 v4, v3, s15, -v4
	v_fmac_f32_e32 v4, 0x3377d1cf, v3
	v_fmac_f32_e32 v4, 0x3f317217, v3
	v_cmp_lt_f32_e64 s[0:1], |v3|, s7
	s_nop 1
	v_cndmask_b32_e64 v3, v3, v4, s[0:1]
	v_cndmask_b32_e32 v4, 0, v230, vcc
	v_sub_f32_e32 v3, v3, v4
	v_pk_add_f32 v[0:1], v[0:1], v[2:3]
	s_mov_b32 s0, 0xbd800000
	v_pk_mul_f32 v[0:1], v[0:1], s[0:1] op_sel_hi:[1,0]
; #define LAS __attribute__((address_space(3)))
; __device__ __forceinline__ float logsig(float x) { return -(fmaxf(-x, 0.f) + __logf(1.0f + __expf(-fabsf(x)))); }
; template <int MODE>
; __device__ __forceinline__ void gla_item(const int TID, const Params& p, int l, int ci, int head, LAS unsigned char* lds, const float (&wg)[2][16], const float (&bg)[2], const float (&ngv)[16]) {
;     ...
;     { const int kk = tid & 63, rb = tid >> 6;
; #pragma unroll
;       for (int i = 0; i < 8; ++i) { const int r = rb + 8 * i; float x0 = bg[0], x1 = bg[1]; f32x4 gr[8];
; #pragma unroll
;           for (int j4 = 0; j4 < 8; ++j4) gr[j4] = *(const LAS f32x4*)(glr_s + r * 32 + j4 * 4);
; #pragma unroll
;           for (int j = 0; j < 16; ++j) { x0 += gr[j >> 2][j & 3] * wg[0][j]; x1 += gr[4 + (j >> 2)][j & 3] * wg[1][j]; }
;           const bool ok = r >= rmin; bfs[r * 64 + kk] = ok ? logsig(x0) * 0.0625f : 0.f; bbs[r * 64 + kk] = ok ? logsig(x1) * 0.0625f : 0.f; } }
.LBB0_755:
	s_or_b64 exec, exec, s[60:61]
	ds_write2st64_b32 v136, v0, v1 offset0:64 offset1:128
	v_cmp_le_i32_e32 vcc, s3, v137
	v_mov_b32_e32 v0, 0
	v_mov_b32_e32 v2, 0
	v_mov_b32_e32 v3, 0
	s_and_saveexec_b64 s[60:61], vcc
	s_cbranch_execz .LBB0_757
	ds_read_b128 v[2:5], v167 offset:112
	s_mov_b32 s8, 0xbfb8aa3b
	s_waitcnt lgkmcnt(0)
	v_pk_mul_f32 v[8:9], v[32:33], v[4:5]
	v_pk_mul_f32 v[10:11], v[38:39], v[2:3]
	ds_read_b128 v[2:5], v167 offset:96
	s_waitcnt lgkmcnt(0)
	v_pk_mul_f32 v[12:13], v[42:43], v[4:5]
	v_pk_mul_f32 v[98:99], v[44:45], v[2:3]
	ds_read_b128 v[2:5], v167 offset:80
	s_waitcnt lgkmcnt(0)
	v_pk_mul_f32 v[100:101], v[40:41], v[4:5]
	ds_read_b128 v[4:7], v167 offset:64
	s_waitcnt lgkmcnt(0)
	v_fma_f32 v1, v124, v4, v122
	v_fmac_f32_e32 v1, v125, v5
	v_fmac_f32_e32 v1, v126, v6
	v_fmac_f32_e32 v1, v127, v7
	v_fmac_f32_e32 v1, v129, v2
	v_fmac_f32_e32 v1, v128, v3
	v_add_f32_e32 v1, v100, v1
	v_add_f32_e32 v1, v101, v1
	v_add_f32_e32 v1, v98, v1
	v_add_f32_e32 v1, v99, v1
	v_add_f32_e32 v1, v12, v1
	v_add_f32_e32 v1, v13, v1
	v_add_f32_e32 v1, v10, v1
	v_add_f32_e32 v1, v11, v1
	v_add_f32_e32 v1, v8, v1
	v_add_f32_e32 v1, v9, v1
	ds_read_b128 v[2:5], v167
	ds_read_b128 v[6:9], v167 offset:16
	ds_read_b128 v[10:13], v167 offset:32
	ds_read_b128 v[98:101], v167 offset:48
	s_waitcnt lgkmcnt(3)
	v_fma_f32 v97, v2, v117, v116
	v_fmac_f32_e32 v97, v3, v118
	v_fmac_f32_e32 v97, v4, v119
	v_fmac_f32_e32 v97, v5, v120
	s_waitcnt lgkmcnt(2)
	v_fmac_f32_e32 v97, v6, v123
	v_fmac_f32_e32 v97, v7, v121
	v_pk_mul_f32 v[2:3], v[8:9], v[30:31]
	s_nop 0
	v_add_f32_e32 v2, v97, v2
	v_add_f32_e32 v4, v2, v3
	s_waitcnt lgkmcnt(1)
	v_pk_mul_f32 v[2:3], v[10:11], v[48:49]
	s_nop 0
	v_add_f32_e32 v2, v4, v2
	v_add_f32_e32 v4, v2, v3
	v_pk_mul_f32 v[2:3], v[12:13], v[46:47]
	s_nop 0
	v_add_f32_e32 v2, v4, v2
	v_add_f32_e32 v4, v2, v3
	s_waitcnt lgkmcnt(0)
	v_pk_mul_f32 v[2:3], v[98:99], v[36:37]
	s_nop 0
	v_add_f32_e32 v2, v4, v2
	v_add_f32_e32 v4, v2, v3
	v_pk_mul_f32 v[2:3], v[100:101], v[34:35]
	s_nop 0
	v_add_f32_e32 v2, v4, v2
	v_add_f32_e32 v3, v2, v3
	v_max_f32_e64 v2, -v3, 0
	v_mul_f32_e64 v3, |v3|, s8
	v_exp_f32_e32 v3, v3
	s_nop 0
	v_add_f32_e32 v3, 1.0, v3
	v_cmp_gt_f32_e32 vcc, s19, v3
	s_nop 1
	v_cndmask_b32_e64 v4, 0, 32, vcc
	v_ldexp_f32 v3, v3, v4
	v_log_f32_e32 v3, v3
	s_nop 0
	v_mul_f32_e32 v4, 0x3f317217, v3
	v_fma_f32 v4, v3, s15, -v4
	v_fmac_f32_e32 v4, 0x3377d1cf, v3
	v_fmac_f32_e32 v4, 0x3f317217, v3
	v_cmp_lt_f32_e64 s[0:1], |v3|, s7
	s_nop 1
	v_cndmask_b32_e64 v3, v3, v4, s[0:1]
	v_cndmask_b32_e32 v4, 0, v230, vcc
	v_sub_f32_e32 v4, v3, v4
	v_max_f32_e64 v3, -v1, 0
	v_mul_f32_e64 v1, |v1|, s8
	v_exp_f32_e32 v1, v1
	s_nop 0
	v_add_f32_e32 v1, 1.0, v1
	v_cmp_gt_f32_e32 vcc, s19, v1
	s_nop 1
	v_cndmask_b32_e64 v5, 0, 32, vcc
	v_ldexp_f32 v1, v1, v5
	v_log_f32_e32 v1, v1
	s_nop 0
	v_mul_f32_e32 v5, 0x3f317217, v1
	v_fma_f32 v5, v1, s15, -v5
	v_fmac_f32_e32 v5, 0x3377d1cf, v1
	v_fmac_f32_e32 v5, 0x3f317217, v1
	v_cmp_lt_f32_e64 s[0:1], |v1|, s7
	s_nop 1
	v_cndmask_b32_e64 v1, v1, v5, s[0:1]
	v_cndmask_b32_e32 v5, 0, v230, vcc
	v_sub_f32_e32 v5, v1, v5
	v_pk_add_f32 v[2:3], v[2:3], v[4:5]
	s_mov_b32 s0, 0xbd800000
	v_pk_mul_f32 v[2:3], v[2:3], s[0:1] op_sel_hi:[1,0]
.LBB0_757:
	s_or_b64 exec, exec, s[60:61]
	v_cmp_le_i32_e32 vcc, s3, v139
	v_mov_b32_e32 v1, 0
	ds_write2st64_b32 v138, v2, v3 offset0:64 offset1:128
	s_and_saveexec_b64 s[60:61], vcc
	s_cbranch_execz .LBB0_759
	ds_read_b128 v[0:3], v168 offset:112
	s_mov_b32 s8, 0xbfb8aa3b
	s_waitcnt lgkmcnt(0)
	v_pk_mul_f32 v[6:7], v[32:33], v[2:3]
	v_pk_mul_f32 v[8:9], v[38:39], v[0:1]
	ds_read_b128 v[0:3], v168 offset:96
	s_waitcnt lgkmcnt(0)
	v_pk_mul_f32 v[10:11], v[42:43], v[2:3]
	v_pk_mul_f32 v[12:13], v[44:45], v[0:1]
	ds_read_b128 v[0:3], v168 offset:80
	s_waitcnt lgkmcnt(0)
	v_pk_mul_f32 v[98:99], v[40:41], v[2:3]
	ds_read_b128 v[2:5], v168 offset:64
	s_waitcnt lgkmcnt(0)
	v_fma_f32 v2, v124, v2, v122
	v_fmac_f32_e32 v2, v125, v3
	v_fmac_f32_e32 v2, v126, v4
	v_fmac_f32_e32 v2, v127, v5
	v_fmac_f32_e32 v2, v129, v0
	v_fmac_f32_e32 v2, v128, v1
	v_add_f32_e32 v0, v98, v2
	v_add_f32_e32 v0, v99, v0
	v_add_f32_e32 v0, v12, v0
	v_add_f32_e32 v0, v13, v0
	v_add_f32_e32 v0, v10, v0
	v_add_f32_e32 v0, v11, v0
	v_add_f32_e32 v0, v8, v0
	v_add_f32_e32 v0, v9, v0
	v_add_f32_e32 v0, v6, v0
	v_add_f32_e32 v12, v7, v0
	ds_read_b128 v[0:3], v168
	ds_read_b128 v[4:7], v168 offset:16
	ds_read_b128 v[8:11], v168 offset:32
	ds_read_b128 v[98:101], v168 offset:48
	s_waitcnt lgkmcnt(3)
	v_fma_f32 v13, v0, v117, v116
	v_fmac_f32_e32 v13, v1, v118
	v_fmac_f32_e32 v13, v2, v119
	v_fmac_f32_e32 v13, v3, v120
	s_waitcnt lgkmcnt(2)
	v_fmac_f32_e32 v13, v4, v123
	v_fmac_f32_e32 v13, v5, v121
	v_pk_mul_f32 v[0:1], v[6:7], v[30:31]
	v_mul_f32_e64 v3, |v12|, s8
	v_add_f32_e32 v0, v13, v0
	v_add_f32_e32 v2, v0, v1
	s_waitcnt lgkmcnt(1)
	v_pk_mul_f32 v[0:1], v[8:9], v[48:49]
	v_exp_f32_e32 v3, v3
	v_add_f32_e32 v0, v2, v0
	v_add_f32_e32 v2, v0, v1
	v_pk_mul_f32 v[0:1], v[10:11], v[46:47]
	v_add_f32_e32 v3, 1.0, v3
	v_add_f32_e32 v0, v2, v0
	v_add_f32_e32 v2, v0, v1
	s_waitcnt lgkmcnt(0)
	v_pk_mul_f32 v[0:1], v[98:99], v[36:37]
	s_nop 0
	v_add_f32_e32 v0, v2, v0
	v_add_f32_e32 v2, v0, v1
	v_pk_mul_f32 v[0:1], v[100:101], v[34:35]
	s_nop 0
	v_add_f32_e32 v0, v2, v0
	v_add_f32_e32 v1, v0, v1
	v_max_f32_e64 v0, -v1, 0
	v_mul_f32_e64 v1, |v1|, s8
	v_exp_f32_e32 v1, v1
	s_nop 0
	v_add_f32_e32 v1, 1.0, v1
	v_cmp_gt_f32_e32 vcc, s19, v1
	s_nop 1
	v_cndmask_b32_e64 v2, 0, 32, vcc
	v_ldexp_f32 v1, v1, v2
	v_log_f32_e32 v1, v1
	s_nop 0
	v_mul_f32_e32 v2, 0x3f317217, v1
	v_fma_f32 v2, v1, s15, -v2
	v_fmac_f32_e32 v2, 0x3377d1cf, v1
	v_fmac_f32_e32 v2, 0x3f317217, v1
	v_cmp_lt_f32_e64 s[0:1], |v1|, s7
	s_nop 1
	v_cndmask_b32_e64 v1, v1, v2, s[0:1]
	v_cndmask_b32_e32 v2, 0, v230, vcc
	v_cmp_gt_f32_e32 vcc, s19, v3
	v_sub_f32_e32 v2, v1, v2
	v_max_f32_e64 v1, -v12, 0
	v_cndmask_b32_e64 v4, 0, 32, vcc
	v_ldexp_f32 v3, v3, v4
	v_log_f32_e32 v3, v3
	s_nop 0
	v_mul_f32_e32 v4, 0x3f317217, v3
	v_fma_f32 v4, v3, s15, -v4
	v_fmac_f32_e32 v4, 0x3377d1cf, v3
	v_fmac_f32_e32 v4, 0x3f317217, v3
	v_cmp_lt_f32_e64 s[0:1], |v3|, s7
	s_nop 1
	v_cndmask_b32_e64 v3, v3, v4, s[0:1]
	v_cndmask_b32_e32 v4, 0, v230, vcc
	v_sub_f32_e32 v3, v3, v4
	v_pk_add_f32 v[0:1], v[0:1], v[2:3]
	s_mov_b32 s0, 0xbd800000
	v_pk_mul_f32 v[0:1], v[0:1], s[0:1] op_sel_hi:[1,0]
; #define LAS __attribute__((address_space(3)))
; __device__ __forceinline__ float logsig(float x) { return -(fmaxf(-x, 0.f) + __logf(1.0f + __expf(-fabsf(x)))); }
; template <int MODE>
; __device__ __forceinline__ void gla_item(const int TID, const Params& p, int l, int ci, int head, LAS unsigned char* lds, const float (&wg)[2][16], const float (&bg)[2], const float (&ngv)[16]) {
;     ...
;     { const int kk = tid & 63, rb = tid >> 6;
; #pragma unroll
;       for (int i = 0; i < 8; ++i) { const int r = rb + 8 * i; float x0 = bg[0], x1 = bg[1]; f32x4 gr[8];
; #pragma unroll
;           for (int j4 = 0; j4 < 8; ++j4) gr[j4] = *(const LAS f32x4*)(glr_s + r * 32 + j4 * 4);
; #pragma unroll
;           for (int j = 0; j < 16; ++j) { x0 += gr[j >> 2][j & 3] * wg[0][j]; x1 += gr[4 + (j >> 2)][j & 3] * wg[1][j]; }
;           const bool ok = r >= rmin; bfs[r * 64 + kk] = ok ? logsig(x0) * 0.0625f : 0.f; bbs[r * 64 + kk] = ok ? logsig(x1) * 0.0625f : 0.f; } }
.LBB0_759:
	s_or_b64 exec, exec, s[60:61]
	ds_write2st64_b32 v140, v0, v1 offset0:64 offset1:128
	v_cmp_le_i32_e32 vcc, s3, v141
	v_mov_b32_e32 v0, 0
	v_mov_b32_e32 v2, 0
	v_mov_b32_e32 v3, 0
	s_and_saveexec_b64 s[60:61], vcc
	s_cbranch_execz .LBB0_761
	ds_read_b128 v[2:5], v169 offset:112
	s_mov_b32 s8, 0xbfb8aa3b
	s_waitcnt lgkmcnt(0)
	v_pk_mul_f32 v[8:9], v[32:33], v[4:5]
	v_pk_mul_f32 v[10:11], v[38:39], v[2:3]
	ds_read_b128 v[2:5], v169 offset:96
	s_waitcnt lgkmcnt(0)
	v_pk_mul_f32 v[12:13], v[42:43], v[4:5]
	v_pk_mul_f32 v[98:99], v[44:45], v[2:3]
	ds_read_b128 v[2:5], v169 offset:80
	s_waitcnt lgkmcnt(0)
	v_pk_mul_f32 v[100:101], v[40:41], v[4:5]
	ds_read_b128 v[4:7], v169 offset:64
	s_waitcnt lgkmcnt(0)
	v_fma_f32 v1, v124, v4, v122
	v_fmac_f32_e32 v1, v125, v5
	v_fmac_f32_e32 v1, v126, v6
	v_fmac_f32_e32 v1, v127, v7
	v_fmac_f32_e32 v1, v129, v2
	v_fmac_f32_e32 v1, v128, v3
	v_add_f32_e32 v1, v100, v1
	v_add_f32_e32 v1, v101, v1
	v_add_f32_e32 v1, v98, v1
	v_add_f32_e32 v1, v99, v1
	v_add_f32_e32 v1, v12, v1
	v_add_f32_e32 v1, v13, v1
	v_add_f32_e32 v1, v10, v1
	v_add_f32_e32 v1, v11, v1
	v_add_f32_e32 v1, v8, v1
	v_add_f32_e32 v1, v9, v1
	ds_read_b128 v[2:5], v169
	ds_read_b128 v[6:9], v169 offset:16
	ds_read_b128 v[10:13], v169 offset:32
	ds_read_b128 v[98:101], v169 offset:48
	s_waitcnt lgkmcnt(3)
	v_fma_f32 v97, v2, v117, v116
	v_fmac_f32_e32 v97, v3, v118
	v_fmac_f32_e32 v97, v4, v119
	v_fmac_f32_e32 v97, v5, v120
	s_waitcnt lgkmcnt(2)
	v_fmac_f32_e32 v97, v6, v123
	v_fmac_f32_e32 v97, v7, v121
	v_pk_mul_f32 v[2:3], v[8:9], v[30:31]
	s_nop 0
	v_add_f32_e32 v2, v97, v2
	v_add_f32_e32 v4, v2, v3
	s_waitcnt lgkmcnt(1)
	v_pk_mul_f32 v[2:3], v[10:11], v[48:49]
	s_nop 0
	v_add_f32_e32 v2, v4, v2
	v_add_f32_e32 v4, v2, v3
	v_pk_mul_f32 v[2:3], v[12:13], v[46:47]
	s_nop 0
	v_add_f32_e32 v2, v4, v2
	v_add_f32_e32 v4, v2, v3
	s_waitcnt lgkmcnt(0)
	v_pk_mul_f32 v[2:3], v[98:99], v[36:37]
	s_nop 0
	v_add_f32_e32 v2, v4, v2
	v_add_f32_e32 v4, v2, v3
	v_pk_mul_f32 v[2:3], v[100:101], v[34:35]
	s_nop 0
	v_add_f32_e32 v2, v4, v2
	v_add_f32_e32 v3, v2, v3
	v_max_f32_e64 v2, -v3, 0
	v_mul_f32_e64 v3, |v3|, s8
	v_exp_f32_e32 v3, v3
	s_nop 0
	v_add_f32_e32 v3, 1.0, v3
	v_cmp_gt_f32_e32 vcc, s19, v3
	s_nop 1
	v_cndmask_b32_e64 v4, 0, 32, vcc
	v_ldexp_f32 v3, v3, v4
	v_log_f32_e32 v3, v3
	s_nop 0
	v_mul_f32_e32 v4, 0x3f317217, v3
	v_fma_f32 v4, v3, s15, -v4
	v_fmac_f32_e32 v4, 0x3377d1cf, v3
	v_fmac_f32_e32 v4, 0x3f317217, v3
	v_cmp_lt_f32_e64 s[0:1], |v3|, s7
	s_nop 1
	v_cndmask_b32_e64 v3, v3, v4, s[0:1]
	v_cndmask_b32_e32 v4, 0, v230, vcc
	v_sub_f32_e32 v4, v3, v4
	v_max_f32_e64 v3, -v1, 0
	v_mul_f32_e64 v1, |v1|, s8
	v_exp_f32_e32 v1, v1
	s_nop 0
	v_add_f32_e32 v1, 1.0, v1
	v_cmp_gt_f32_e32 vcc, s19, v1
	s_nop 1
	v_cndmask_b32_e64 v5, 0, 32, vcc
	v_ldexp_f32 v1, v1, v5
	v_log_f32_e32 v1, v1
	s_nop 0
	v_mul_f32_e32 v5, 0x3f317217, v1
	v_fma_f32 v5, v1, s15, -v5
	v_fmac_f32_e32 v5, 0x3377d1cf, v1
	v_fmac_f32_e32 v5, 0x3f317217, v1
	v_cmp_lt_f32_e64 s[0:1], |v1|, s7
	s_nop 1
	v_cndmask_b32_e64 v1, v1, v5, s[0:1]
	v_cndmask_b32_e32 v5, 0, v230, vcc
	v_sub_f32_e32 v5, v1, v5
	v_pk_add_f32 v[2:3], v[2:3], v[4:5]
	s_mov_b32 s0, 0xbd800000
	v_pk_mul_f32 v[2:3], v[2:3], s[0:1] op_sel_hi:[1,0]
; #define LAS __attribute__((address_space(3)))
; __device__ __forceinline__ float logsig(float x) { return -(fmaxf(-x, 0.f) + __logf(1.0f + __expf(-fabsf(x)))); }
; template <int MODE>
; __device__ __forceinline__ void gla_item(const int TID, const Params& p, int l, int ci, int head, LAS unsigned char* lds, const float (&wg)[2][16], const float (&bg)[2], const float (&ngv)[16]) {
;     ...
;     { const int kk = tid & 63, rb = tid >> 6;
; #pragma unroll
;       for (int i = 0; i < 8; ++i) { const int r = rb + 8 * i; float x0 = bg[0], x1 = bg[1]; f32x4 gr[8];
; #pragma unroll
;           for (int j4 = 0; j4 < 8; ++j4) gr[j4] = *(const LAS f32x4*)(glr_s + r * 32 + j4 * 4);
; #pragma unroll
;           for (int j = 0; j < 16; ++j) { x0 += gr[j >> 2][j & 3] * wg[0][j]; x1 += gr[4 + (j >> 2)][j & 3] * wg[1][j]; }
;           const bool ok = r >= rmin; bfs[r * 64 + kk] = ok ? logsig(x0) * 0.0625f : 0.f; bbs[r * 64 + kk] = ok ? logsig(x1) * 0.0625f : 0.f; } }
.LBB0_761:
	s_or_b64 exec, exec, s[60:61]
	v_cmp_le_i32_e32 vcc, s3, v145
	v_mov_b32_e32 v1, 0
	ds_write2st64_b32 v144, v2, v3 offset0:64 offset1:128
	s_and_saveexec_b64 s[60:61], vcc
	s_cbranch_execz .LBB0_763
	ds_read_b128 v[0:3], v170 offset:112
	s_mov_b32 s8, 0xbfb8aa3b
	s_waitcnt lgkmcnt(0)
	v_pk_mul_f32 v[6:7], v[32:33], v[2:3]
	v_pk_mul_f32 v[8:9], v[38:39], v[0:1]
	ds_read_b128 v[0:3], v170 offset:96
	s_waitcnt lgkmcnt(0)
	v_pk_mul_f32 v[10:11], v[42:43], v[2:3]
	v_pk_mul_f32 v[12:13], v[44:45], v[0:1]
	ds_read_b128 v[0:3], v170 offset:80
	s_waitcnt lgkmcnt(0)
	v_pk_mul_f32 v[98:99], v[40:41], v[2:3]
	ds_read_b128 v[2:5], v170 offset:64
	s_waitcnt lgkmcnt(0)
	v_fma_f32 v2, v124, v2, v122
	v_fmac_f32_e32 v2, v125, v3
	v_fmac_f32_e32 v2, v126, v4
	v_fmac_f32_e32 v2, v127, v5
	v_fmac_f32_e32 v2, v129, v0
	v_fmac_f32_e32 v2, v128, v1
	v_add_f32_e32 v0, v98, v2
	v_add_f32_e32 v0, v99, v0
	v_add_f32_e32 v0, v12, v0
	v_add_f32_e32 v0, v13, v0
	v_add_f32_e32 v0, v10, v0
	v_add_f32_e32 v0, v11, v0
	v_add_f32_e32 v0, v8, v0
	v_add_f32_e32 v0, v9, v0
	v_add_f32_e32 v0, v6, v0
	v_add_f32_e32 v12, v7, v0
	ds_read_b128 v[0:3], v170
	ds_read_b128 v[4:7], v170 offset:16
	ds_read_b128 v[8:11], v170 offset:32
	ds_read_b128 v[98:101], v170 offset:48
	s_waitcnt lgkmcnt(3)
	v_fma_f32 v13, v0, v117, v116
	v_fmac_f32_e32 v13, v1, v118
	v_fmac_f32_e32 v13, v2, v119
	v_fmac_f32_e32 v13, v3, v120
	s_waitcnt lgkmcnt(2)
	v_fmac_f32_e32 v13, v4, v123
	v_fmac_f32_e32 v13, v5, v121
	v_pk_mul_f32 v[0:1], v[6:7], v[30:31]
	v_mul_f32_e64 v3, |v12|, s8
	v_add_f32_e32 v0, v13, v0
	v_add_f32_e32 v2, v0, v1
	s_waitcnt lgkmcnt(1)
	v_pk_mul_f32 v[0:1], v[8:9], v[48:49]
	v_exp_f32_e32 v3, v3
	v_add_f32_e32 v0, v2, v0
	v_add_f32_e32 v2, v0, v1
	v_pk_mul_f32 v[0:1], v[10:11], v[46:47]
	v_add_f32_e32 v3, 1.0, v3
	v_add_f32_e32 v0, v2, v0
	v_add_f32_e32 v2, v0, v1
	s_waitcnt lgkmcnt(0)
	v_pk_mul_f32 v[0:1], v[98:99], v[36:37]
	s_nop 0
	v_add_f32_e32 v0, v2, v0
	v_add_f32_e32 v2, v0, v1
	v_pk_mul_f32 v[0:1], v[100:101], v[34:35]
	s_nop 0
	v_add_f32_e32 v0, v2, v0
	v_add_f32_e32 v1, v0, v1
	v_max_f32_e64 v0, -v1, 0
	v_mul_f32_e64 v1, |v1|, s8
	v_exp_f32_e32 v1, v1
	s_nop 0
	v_add_f32_e32 v1, 1.0, v1
	v_cmp_gt_f32_e32 vcc, s19, v1
	s_nop 1
	v_cndmask_b32_e64 v2, 0, 32, vcc
	v_ldexp_f32 v1, v1, v2
	v_log_f32_e32 v1, v1
	s_nop 0
	v_mul_f32_e32 v2, 0x3f317217, v1
	v_fma_f32 v2, v1, s15, -v2
	v_fmac_f32_e32 v2, 0x3377d1cf, v1
	v_fmac_f32_e32 v2, 0x3f317217, v1
	v_cmp_lt_f32_e64 s[0:1], |v1|, s7
	s_nop 1
	v_cndmask_b32_e64 v1, v1, v2, s[0:1]
	v_cndmask_b32_e32 v2, 0, v230, vcc
	v_cmp_gt_f32_e32 vcc, s19, v3
	v_sub_f32_e32 v2, v1, v2
	v_max_f32_e64 v1, -v12, 0
	v_cndmask_b32_e64 v4, 0, 32, vcc
	v_ldexp_f32 v3, v3, v4
	v_log_f32_e32 v3, v3
	s_nop 0
	v_mul_f32_e32 v4, 0x3f317217, v3
	v_fma_f32 v4, v3, s15, -v4
	v_fmac_f32_e32 v4, 0x3377d1cf, v3
	v_fmac_f32_e32 v4, 0x3f317217, v3
	v_cmp_lt_f32_e64 s[0:1], |v3|, s7
	s_nop 1
	v_cndmask_b32_e64 v3, v3, v4, s[0:1]
	v_cndmask_b32_e32 v4, 0, v230, vcc
	v_sub_f32_e32 v3, v3, v4
	v_pk_add_f32 v[0:1], v[0:1], v[2:3]
	s_mov_b32 s0, 0xbd800000
	v_pk_mul_f32 v[0:1], v[0:1], s[0:1] op_sel_hi:[1,0]
.LBB0_763:
	s_or_b64 exec, exec, s[60:61]
	ds_write2st64_b32 v146, v0, v1 offset0:64 offset1:128
	v_cmp_le_i32_e32 vcc, s3, v147
	v_mov_b32_e32 v0, 0
	v_mov_b32_e32 v1, 0
	s_and_saveexec_b64 s[60:61], vcc
	s_cbranch_execz .LBB0_765
	ds_read_b128 v[0:3], v171 offset:112
	s_mov_b32 s3, 0xbfb8aa3b
	s_waitcnt lgkmcnt(0)
	v_pk_mul_f32 v[6:7], v[32:33], v[2:3]
	v_pk_mul_f32 v[8:9], v[38:39], v[0:1]
	ds_read_b128 v[0:3], v171 offset:96
	s_waitcnt lgkmcnt(0)
	v_pk_mul_f32 v[10:11], v[42:43], v[2:3]
	v_pk_mul_f32 v[12:13], v[44:45], v[0:1]
	ds_read_b128 v[0:3], v171 offset:80
	s_waitcnt lgkmcnt(0)
	v_pk_mul_f32 v[98:99], v[40:41], v[2:3]
	ds_read_b128 v[2:5], v171 offset:64
	s_waitcnt lgkmcnt(0)
	v_fma_f32 v2, v124, v2, v122
	v_fmac_f32_e32 v2, v125, v3
	v_fmac_f32_e32 v2, v126, v4
	v_fmac_f32_e32 v2, v127, v5
	v_fmac_f32_e32 v2, v129, v0
	v_fmac_f32_e32 v2, v128, v1
	v_add_f32_e32 v0, v98, v2
	v_add_f32_e32 v0, v99, v0
	v_add_f32_e32 v0, v12, v0
	v_add_f32_e32 v0, v13, v0
	v_add_f32_e32 v0, v10, v0
	v_add_f32_e32 v0, v11, v0
	v_add_f32_e32 v0, v8, v0
	v_add_f32_e32 v0, v9, v0
	v_add_f32_e32 v0, v6, v0
	v_add_f32_e32 v12, v7, v0
	ds_read_b128 v[0:3], v171
	ds_read_b128 v[4:7], v171 offset:16
	ds_read_b128 v[8:11], v171 offset:32
	ds_read_b128 v[98:101], v171 offset:48
	s_waitcnt lgkmcnt(3)
	v_fma_f32 v13, v0, v117, v116
	v_fmac_f32_e32 v13, v1, v118
	v_fmac_f32_e32 v13, v2, v119
	v_fmac_f32_e32 v13, v3, v120
	s_waitcnt lgkmcnt(2)
	v_fmac_f32_e32 v13, v4, v123
	v_fmac_f32_e32 v13, v5, v121
	v_pk_mul_f32 v[0:1], v[6:7], v[30:31]
	v_mul_f32_e64 v3, |v12|, s3
	v_add_f32_e32 v0, v13, v0
	v_add_f32_e32 v2, v0, v1
	s_waitcnt lgkmcnt(1)
	v_pk_mul_f32 v[0:1], v[8:9], v[48:49]
	v_exp_f32_e32 v3, v3
	v_add_f32_e32 v0, v2, v0
	v_add_f32_e32 v2, v0, v1
	v_pk_mul_f32 v[0:1], v[10:11], v[46:47]
	v_add_f32_e32 v3, 1.0, v3
	v_add_f32_e32 v0, v2, v0
	v_add_f32_e32 v2, v0, v1
	s_waitcnt lgkmcnt(0)
	v_pk_mul_f32 v[0:1], v[98:99], v[36:37]
	s_nop 0
	v_add_f32_e32 v0, v2, v0
	v_add_f32_e32 v2, v0, v1
	v_pk_mul_f32 v[0:1], v[100:101], v[34:35]
	s_nop 0
	v_add_f32_e32 v0, v2, v0
	v_add_f32_e32 v1, v0, v1
	v_max_f32_e64 v0, -v1, 0
	v_mul_f32_e64 v1, |v1|, s3
	v_exp_f32_e32 v1, v1
	s_nop 0
	v_add_f32_e32 v1, 1.0, v1
	v_cmp_gt_f32_e32 vcc, s19, v1
	s_nop 1
	v_cndmask_b32_e64 v2, 0, 32, vcc
	v_ldexp_f32 v1, v1, v2
	v_log_f32_e32 v1, v1
	s_nop 0
	v_mul_f32_e32 v2, 0x3f317217, v1
	v_fma_f32 v2, v1, s15, -v2
	v_fmac_f32_e32 v2, 0x3377d1cf, v1
	v_fmac_f32_e32 v2, 0x3f317217, v1
	v_cmp_lt_f32_e64 s[0:1], |v1|, s7
	s_nop 1
	v_cndmask_b32_e64 v1, v1, v2, s[0:1]
	v_cndmask_b32_e32 v2, 0, v230, vcc
	v_cmp_gt_f32_e32 vcc, s19, v3
	v_sub_f32_e32 v2, v1, v2
	v_max_f32_e64 v1, -v12, 0
	v_cndmask_b32_e64 v4, 0, 32, vcc
	v_ldexp_f32 v3, v3, v4
	v_log_f32_e32 v3, v3
	s_nop 0
	v_mul_f32_e32 v4, 0x3f317217, v3
	v_fma_f32 v4, v3, s15, -v4
	v_fmac_f32_e32 v4, 0x3377d1cf, v3
	v_fmac_f32_e32 v4, 0x3f317217, v3
	v_cmp_lt_f32_e64 s[0:1], |v3|, s7
	s_nop 1
	v_cndmask_b32_e64 v3, v3, v4, s[0:1]
	v_cndmask_b32_e32 v4, 0, v230, vcc
	v_sub_f32_e32 v3, v3, v4
	v_pk_add_f32 v[0:1], v[0:1], v[2:3]
	s_mov_b32 s0, 0xbd800000
	v_pk_mul_f32 v[0:1], v[0:1], s[0:1] op_sel_hi:[1,0]
